# mqk: activation rows pulled one 128-byte column at a time (first column before the loop, the next ones from inside the channel loop) instead of a bulk 256 KiB pull
# speedup vs baseline: 1.0080x; 1.0080x over previous
; __device__ __forceinline__ void unpack8(u32x4 w, float* f) { f[0] = bflo(w.x); f[1] = bfhi(w.x); f[2] = bflo(w.y); f[3] = bfhi(w.y); f[4] = bflo(w.z); f[5] = bfhi(w.z); f[6] = bflo(w.w); f[7] = bfhi(w.w); }
; __device__ void mqk_phase(const Params& p, unsigned char* smem) {
;     ...
;     for (int tile = blockIdx.x; tile < 256; tile += gridDim.x) {
;         const int row0 = tile * 64;
;         f32x4 acc[4];
; #pragma unroll
;         for (int m = 0; m < 4; ++m) acc[m] = (f32x4){0.f, 0.f, 0.f, 0.f};
;         for (int ks = 0; ks < 8; ++ks) {
;             const int c0 = 256 * wave + 32 * ks + 8 * (lane >> 4);
;             float cw[4][8], cbv[8];
; #pragma unroll
;             for (int j = 0; j < 4; ++j) { const f32x4 a = *(const f32x4*)(p.in[10] + j * 2048 + c0), b = *(const f32x4*)(p.in[10] + j * 2048 + c0 + 4);
; #pragma unroll
;                 for (int i = 0; i < 4; ++i) { cw[j][i] = a[i]; cw[j][4 + i] = b[i]; } }
;             { const f32x4 a = *(const f32x4*)(p.in[11] + c0), b = *(const f32x4*)(p.in[11] + c0 + 4);
; #pragma unroll
;               for (int i = 0; i < 4; ++i) { cbv[i] = a[i]; cbv[4 + i] = b[i]; } }
;             const bf16x8 bq = *(const bf16x8*)(WG + (size_t)(lane & 15) * 6144 + c0), bk = *(const bf16x8*)(WG + (size_t)(lane & 15) * 6144 + 2048 + c0), bv = *(const bf16x8*)(WG + (size_t)(lane & 15) * 6144 + 4096 + c0);
;             const float* wqp = p.in[12] + (size_t)(c0 >> 2) * 16; const float* wkp = p.in[13] + (size_t)(c0 >> 2) * 16; const float* wvp = p.in[14] + (size_t)(c0 >> 2) * 16;
;             u32x4 xraw[4];
;     ...
;             MQ_LOAD(xraw, 0);
; #pragma unroll
;             for (int m = 0; m < 4; ++m) {
;                 const int tk = row0 + 16 * m + (lane & 15);
;                 u32x4 xnx[4];
;                 if (m < 3) MQ_LOAD(xnx, m + 1);
;                 float xmc[8], xcur[8];
; #pragma unroll
;                 for (int i = 0; i < 8; ++i) xmc[i] = cbv[i];
; #pragma unroll
;                 for (int j = 0; j < 4; ++j) { float xv[8]; unpack8(xraw[j], xv);
; #pragma unroll
;                     for (int i = 0; i < 8; ++i) { xmc[i] += cw[j][i] * xv[i]; if (j == 3) xcur[i] = xv[i]; } }
.LBB0_299:
	v_and_b32_e32 v253, 63, v0
	v_lshlrev_b32_e32 v253, 12, v253
	v_bfe_u32 v254, v0, 6, 3
	v_lshl_add_u32 v253, v254, 9, v253
	s_lshl_b32 s52, s50, 18
	v_add_u32_e32 v253, s52, v253
	global_load_dword v255, v253, s[0:1]
	v_and_b32_e32 v118, 0x3ff, v0
	v_lshlrev_b32_e32 v118, 4, v118
	v_add_u32_e32 v119, 0x2000, v118
	v_add_u32_e32 v120, 0x4000, v118
	v_add_u32_e32 v121, 0x6000, v118
	global_load_dwordx4 v[70:73], v118, s[80:81]
	global_load_dwordx4 v[74:77], v119, s[80:81]
	global_load_dwordx4 v[78:81], v120, s[80:81]
	global_load_dwordx4 v[82:85], v121, s[80:81]
	global_load_dwordx4 v[86:89], v118, s[76:77]
	global_load_dwordx4 v[90:93], v119, s[76:77]
	global_load_dwordx4 v[94:97], v120, s[76:77]
	global_load_dwordx4 v[98:101], v121, s[76:77]
	global_load_dwordx4 v[102:105], v118, s[78:79]
	global_load_dwordx4 v[106:109], v119, s[78:79]
	global_load_dwordx4 v[110:113], v120, s[78:79]
	global_load_dwordx4 v[114:117], v121, s[78:79]
	s_waitcnt vmcnt(0)
	ds_write_b128 v118, v[70:73] offset:32768
	ds_write_b128 v119, v[74:77] offset:32768
	ds_write_b128 v120, v[78:81] offset:32768
	ds_write_b128 v121, v[82:85] offset:32768
	v_add_u32_e32 v118, 0x10000, v118
	v_add_u32_e32 v119, 0x10000, v119
	v_add_u32_e32 v120, 0x10000, v120
	v_add_u32_e32 v121, 0x10000, v121
	ds_write_b128 v118, v[86:89]
	ds_write_b128 v119, v[90:93]
	ds_write_b128 v120, v[94:97]
	ds_write_b128 v121, v[98:101]
	ds_write_b128 v118, v[102:105] offset:32768
	ds_write_b128 v119, v[106:109] offset:32768
	ds_write_b128 v120, v[110:113] offset:32768
	ds_write_b128 v121, v[114:117] offset:32768
	s_waitcnt lgkmcnt(0)
	s_barrier
	s_lshl_b32 s2, s50, 6
	v_or_b32_e32 v2, s2, v229
	v_ashrrev_i32_e32 v3, 31, v2
	v_bitop3_b32 v5, s2, v232, v229 bitop3:0xc8
	v_or_b32_e32 v4, 16, v2
	v_lshlrev_b64 v[174:175], 12, v[2:3]
	v_lshlrev_b64 v[6:7], 11, v[2:3]
	v_or_b32_e32 v8, 32, v2
	v_or_b32_e32 v2, 48, v2
	v_cmp_lt_u32_e32 vcc, 2, v5
	v_cmp_lt_u32_e64 s[2:3], 1, v5
	v_cmp_ne_u32_e64 s[4:5], 0, v5
	v_ashrrev_i32_e32 v5, 31, v4
	v_ashrrev_i32_e32 v9, 31, v8
	v_ashrrev_i32_e32 v3, 31, v2
	v_lshlrev_b64 v[188:189], 12, v[4:5]
	v_lshlrev_b64 v[196:197], 12, v[8:9]
	v_lshlrev_b64 v[4:5], 11, v[4:5]
	v_lshlrev_b64 v[204:205], 12, v[2:3]
	v_lshlrev_b64 v[8:9], 11, v[8:9]
	v_lshlrev_b64 v[2:3], 11, v[2:3]
	v_lshl_add_u64 v[176:177], v[174:175], 0, s[14:15]
	v_lshl_add_u64 v[178:179], v[174:175], 0, s[16:17]
	v_lshl_add_u64 v[180:181], v[174:175], 0, s[18:19]
	v_lshl_add_u64 v[182:183], v[174:175], 0, s[20:21]
	v_lshl_add_u64 v[184:185], v[174:175], 0, s[22:23]
	v_lshl_add_u64 v[186:187], v[174:175], 0, s[24:25]
	v_lshl_add_u64 v[190:191], v[174:175], 0, s[26:27]
	v_lshl_add_u64 v[192:193], v[174:175], 0, s[28:29]
	v_lshl_add_u64 v[194:195], v[174:175], 0, s[30:31]
	v_lshl_add_u64 v[198:199], v[174:175], 0, s[34:35]
	v_lshl_add_u64 v[200:201], v[174:175], 0, s[36:37]
	v_lshl_add_u64 v[202:203], v[174:175], 0, s[38:39]
	v_lshlrev_b64 v[206:207], 1, v[6:7]
	v_lshlrev_b64 v[208:209], 1, v[4:5]
	v_lshlrev_b64 v[210:211], 1, v[8:9]
	v_lshlrev_b64 v[212:213], 1, v[2:3]
	s_mov_b32 s51, 0
	v_mov_b32_e32 v66, v163
	v_mov_b32_e32 v67, v163
	v_mov_b32_e32 v68, v163
	v_mov_b32_e32 v69, v163
	v_mov_b32_e32 v62, v163
	v_mov_b32_e32 v63, v163
	v_mov_b32_e32 v64, v163
	v_mov_b32_e32 v65, v163
	v_mov_b32_e32 v2, v163
	v_mov_b32_e32 v3, v163
	v_mov_b32_e32 v4, v163
	v_mov_b32_e32 v5, v163
	v_mov_b32_e32 v6, v163
	v_mov_b32_e32 v7, v163
	v_mov_b32_e32 v8, v163
	v_mov_b32_e32 v9, v163
	s_branch .LBB0_301
.LBB0_300:
	s_or_b64 exec, exec, s[6:7]
	v_lshl_add_u64 v[70:71], v[224:225], 0, v[174:175]
	global_load_dwordx4 v[98:101], v[70:71], off
	v_lshrrev_b32_e32 v70, 2, v162
	v_mov_b32_e32 v71, v163
	v_lshlrev_b64 v[70:71], 6, v[70:71]
	v_add_u32_e32 v218, 0x8000, v70
	ds_read_b128 v[114:117], v218
	ds_read_b128 v[110:113], v218 offset:16
	s_nop 0
	v_add_u32_e32 v222, 0x18000, v70
	ds_read_b128 v[118:121], v218 offset:32784
	ds_read_b128 v[130:133], v218 offset:32768
	ds_read_b128 v[126:129], v222
	ds_read_b128 v[122:125], v222 offset:16
	ds_read_b128 v[106:109], v218 offset:32
	ds_read_b128 v[102:105], v218 offset:48
	s_nop 0
	s_waitcnt vmcnt(1)
	v_lshlrev_b32_e32 v134, 16, v90
	v_and_b32_e32 v135, 0xffff0000, v90
	v_lshl_add_u64 v[70:71], v[224:225], 0, v[182:183]
	v_lshl_add_u64 v[72:73], v[224:225], 0, v[184:185]
	v_lshl_add_u64 v[82:83], v[224:225], 0, v[186:187]
	v_lshl_add_u64 v[84:85], v[224:225], 0, v[188:189]
	v_lshlrev_b32_e32 v136, 16, v86
	v_and_b32_e32 v137, 0xffff0000, v86
	v_pk_fma_f32 v[134:135], v[46:47], v[134:135], v[58:59]
	global_load_dwordx4 v[78:81], v[70:71], off
	global_load_dwordx4 v[74:77], v[72:73], off
	s_nop 0
	global_load_dwordx4 v[70:73], v[82:83], off
	s_nop 0
	global_load_dwordx4 v[82:85], v[84:85], off
	s_add_i32 s52, s51, 1
	s_lshr_b32 s52, s52, 1
	s_lshl_b32 s52, s52, 7
	v_add_u32_e32 v254, s52, v253
	global_load_dword v255, v254, s[0:1]
	v_pk_fma_f32 v[152:153], v[50:51], v[136:137], v[134:135]
	ds_read_b128 v[142:145], v218 offset:32816
	ds_read_b128 v[146:149], v218 offset:32800
	ds_read_b128 v[134:137], v222 offset:48
	ds_read_b128 v[138:141], v222 offset:32
	v_lshlrev_b32_e32 v150, 16, v94
	v_and_b32_e32 v151, 0xffff0000, v94
	v_pk_fma_f32 v[150:151], v[54:55], v[150:151], v[152:153]
	v_lshlrev_b32_e32 v162, 1, v162
	v_lshl_add_u64 v[216:217], s[10:11], 0, v[162:163]
	v_lshl_add_u64 v[214:215], s[12:13], 0, v[162:163]
	s_add_i32 s51, s51, 1
	s_cmp_eq_u32 s51, 8
	s_nop 0
	s_waitcnt vmcnt(5)
	v_lshlrev_b32_e32 v158, 16, v98
	v_and_b32_e32 v159, 0xffff0000, v98
	v_pk_fma_f32 v[150:151], v[42:43], v[158:159], v[150:151]
	v_lshlrev_b32_e32 v98, 16, v99
	v_mul_f32_e32 v86, 0xbfb8aa3b, v150
	v_mul_f32_e32 v90, 0xbfb8aa3b, v151
	v_exp_f32_e32 v86, v86
	v_exp_f32_e32 v90, v90
	s_nop 0
	s_waitcnt lgkmcnt(11)
; __device__ __forceinline__ u32x4 pack8(const float* f) { u32x4 w; w.x = pk2(f[0], f[1]); w.y = pk2(f[2], f[3]); w.z = pk2(f[4], f[5]); w.w = pk2(f[6], f[7]); return w; }
; #define MFMA16(a, b, c) __builtin_amdgcn_mfma_f32_16x16x32_bf16((a), (b), (c), 0, 0, 0)
; __device__ __forceinline__ float fsig0(float x) { return __builtin_amdgcn_rcpf(1.0f + __expf(-x)); }
; __device__ void mqk_phase(const Params& p, unsigned char* smem) {
;     ...
;                 for (int i = 0; i < 8; ++i) xmc[i] = xmc[i] * fsig0(xmc[i]);
;                 float qv[8], kv[8], vv[8];
; #pragma unroll
;                 for (int bb = 0; bb < 2; ++bb)
; #pragma unroll
;                     for (int jj = 0; jj < 4; ++jj) { float aq = 0.f, ak = 0.f, av = 0.f;
; #pragma unroll
;                         for (int ii = 0; ii < 4; ++ii) { aq += xmc[4 * bb + ii] * wqp[bb * 16 + ii * 4 + jj]; ak += xmc[4 * bb + ii] * wkp[bb * 16 + ii * 4 + jj]; av += xcur[4 * bb + ii] * wvp[bb * 16 + ii * 4 + jj]; }
;                         qv[4 * bb + jj] = aq; kv[4 * bb + jj] = ak; vv[4 * bb + jj] = av; }
;                 const u32x4 qw = pack8(qv), kw = pack8(kv), vw = pack8(vv);
;                 acc[m] = MFMA16(as_frag(qw), bq, acc[m]); acc[m] = MFMA16(as_frag(kw), bk, acc[m]); acc[m] = MFMA16(as_frag(vw), bv, acc[m]);
	v_mov_b32_e32 v152, v114
	s_nop 0
	s_waitcnt lgkmcnt(10)
	v_mov_b32_e32 v153, v110
	v_add_f32_e32 v86, 1.0, v86
	v_add_f32_e32 v90, 1.0, v90
	v_rcp_f32_e32 v226, v86
	v_rcp_f32_e32 v227, v90
	v_mov_b32_e32 v110, v115
	v_mov_b32_e32 v114, v116
	v_mov_b32_e32 v115, v112
	v_pk_mul_f32 v[110:111], v[110:111], v[158:159]
	v_pk_mul_f32 v[114:115], v[114:115], v[158:159]
	s_nop 0
	s_waitcnt lgkmcnt(5)
	v_mov_b32_e32 v160, v106
	v_add_f32_e32 v106, 0, v110
	v_add_f32_e32 v110, 0, v114
	v_mov_b32_e32 v156, v126
	v_mov_b32_e32 v157, v122
	v_add_f32_e32 v90, v106, v111
	v_add_f32_e32 v106, v110, v115
	v_pk_mul_f32 v[110:111], v[150:151], v[226:227]
	v_mov_b32_e32 v154, v130
	v_mov_b32_e32 v155, v118
	v_mov_b32_e32 v118, v131
	v_pk_mul_f32 v[152:153], v[152:153], v[158:159]
	v_pk_mul_f32 v[150:151], v[156:157], v[110:111]
	v_mov_b32_e32 v122, v127
	v_add_f32_e32 v94, 0, v152
	v_pk_mul_f32 v[114:115], v[154:155], v[110:111]
	v_pk_mul_f32 v[118:119], v[110:111], v[118:119]
	v_add_f32_e32 v112, 0, v150
	v_and_b32_e32 v99, 0xffff0000, v99
	v_add_f32_e32 v86, v94, v153
	v_pk_mul_f32 v[122:123], v[110:111], v[122:123]
	v_add_f32_e32 v94, 0, v114
	v_add_f32_e32 v114, 0, v118
	v_add_f32_e32 v112, v151, v112
	s_nop 0
	s_waitcnt lgkmcnt(4)
	v_mov_b32_e32 v161, v102
	ds_read_b128 v[150:153], v218 offset:80
	ds_read_b128 v[154:157], v218 offset:64
	v_add_f32_e32 v116, 0, v122
	v_add_f32_e32 v122, v115, v94
	v_add_f32_e32 v119, v114, v119
	v_pk_mul_f32 v[114:115], v[160:161], v[98:99]
	v_mov_b32_e32 v102, v107
	v_mov_b32_e32 v130, v132
	v_mov_b32_e32 v131, v120
	v_add_f32_e32 v86, v86, v114
	v_pk_mul_f32 v[102:103], v[102:103], v[98:99]
	v_mov_b32_e32 v126, v128
	v_pk_mul_f32 v[130:131], v[110:111], v[130:131]
	v_add_f32_e32 v128, v86, v115
	v_add_f32_e32 v86, v90, v102
	v_lshlrev_b32_e32 v90, 16, v91
	v_and_b32_e32 v91, 0xffff0000, v91
	v_add_f32_e32 v120, 0, v130
	v_add_f32_e32 v130, v86, v103
	v_pk_fma_f32 v[90:91], v[48:49], v[90:91], v[60:61]
	v_lshlrev_b32_e32 v86, 16, v87
	v_and_b32_e32 v87, 0xffff0000, v87
	v_pk_fma_f32 v[86:87], v[52:53], v[86:87], v[90:91]
	v_lshlrev_b32_e32 v90, 16, v95
	v_and_b32_e32 v91, 0xffff0000, v95
	v_pk_fma_f32 v[86:87], v[56:57], v[90:91], v[86:87]
	ds_read_b128 v[234:237], v218 offset:32848
	ds_read_b128 v[238:241], v218 offset:32832
	v_pk_fma_f32 v[86:87], v[44:45], v[98:99], v[86:87]
	v_add_f32_e32 v120, v120, v131
	v_mul_f32_e32 v90, 0xbfb8aa3b, v86
	v_exp_f32_e32 v91, v90
	v_mul_f32_e32 v90, 0xbfb8aa3b, v87
	v_exp_f32_e32 v95, v90
	ds_read_b128 v[242:245], v222 offset:80
	ds_read_b128 v[246:249], v222 offset:64
	v_add_f32_e32 v91, 1.0, v91
	v_rcp_f32_e32 v94, v91
	v_add_f32_e32 v91, 1.0, v95
	v_rcp_f32_e32 v95, v91
	v_mov_b32_e32 v127, v124
	v_add_f32_e32 v116, v116, v123
	v_mov_b32_e32 v90, v108
	v_pk_mul_f32 v[86:87], v[86:87], v[94:95]
	s_nop 0
	s_waitcnt lgkmcnt(8)
	v_mov_b32_e32 v94, v146
	v_mov_b32_e32 v95, v142
	v_pk_mul_f32 v[94:95], v[86:87], v[94:95]
	v_mov_b32_e32 v142, v147
	v_add_f32_e32 v94, v94, v122
	v_add_f32_e32 v131, v94, v95
	s_nop 0
	s_waitcnt lgkmcnt(6)
	v_mov_b32_e32 v94, v138
	v_mov_b32_e32 v95, v134
	v_pk_mul_f32 v[94:95], v[86:87], v[94:95]
	v_mov_b32_e32 v134, v139
	v_add_f32_e32 v94, v112, v94
	v_add_f32_e32 v132, v94, v95
	v_pk_mul_f32 v[94:95], v[86:87], v[142:143]
	v_mov_b32_e32 v91, v104
	v_add_f32_e32 v94, v119, v94
	v_add_f32_e32 v138, v94, v95
	v_pk_mul_f32 v[94:95], v[86:87], v[134:135]
	v_mov_b32_e32 v102, v148
	v_mov_b32_e32 v103, v144
	v_pk_mul_f32 v[126:127], v[110:111], v[126:127]
	v_pk_mul_f32 v[90:91], v[90:91], v[98:99]
	v_add_f32_e32 v94, v116, v94
	v_pk_mul_f32 v[102:103], v[86:87], v[102:103]
	v_add_f32_e32 v118, 0, v126
	v_add_f32_e32 v90, v106, v90
	v_add_f32_e32 v134, v94, v95
	v_mov_b32_e32 v94, v140
	v_mov_b32_e32 v95, v136
	v_add_f32_e32 v102, v120, v102
	v_mov_b32_e32 v120, v133
	v_add_f32_e32 v118, v118, v127
	v_pk_mul_f32 v[94:95], v[86:87], v[94:95]
	v_add_f32_e32 v140, v90, v91
	v_pk_mul_f32 v[90:91], v[110:111], v[120:121]
	v_add_f32_e32 v94, v118, v94
	v_add_f32_e32 v90, 0, v90
	v_mov_b32_e32 v124, v129
	v_add_f32_e32 v139, v94, v95
	v_add_f32_e32 v94, v90, v91
	v_pk_mul_f32 v[90:91], v[110:111], v[124:125]
	v_mov_b32_e32 v112, v117
	v_add_f32_e32 v90, 0, v90
	v_add_f32_e32 v95, v90, v91
	v_pk_mul_f32 v[90:91], v[112:113], v[158:159]
	ds_read_b128 v[110:113], v218 offset:112
	ds_read_b128 v[114:117], v218 offset:96
	v_add_f32_e32 v90, 0, v90
	v_mov_b32_e32 v144, v149
	v_mov_b32_e32 v136, v141
	v_add_f32_e32 v135, v102, v103
	v_add_f32_e32 v102, v90, v91
	v_pk_mul_f32 v[90:91], v[86:87], v[144:145]
	v_pk_mul_f32 v[86:87], v[86:87], v[136:137]
	v_mov_b32_e32 v104, v109
	v_add_f32_e32 v86, v95, v86
	v_add_f32_e32 v133, v86, v87
	v_pk_mul_f32 v[86:87], v[104:105], v[98:99]
	v_add_f32_e32 v90, v94, v90
	v_add_f32_e32 v86, v102, v86
	ds_read_b128 v[102:105], v218 offset:32880
	ds_read_b128 v[106:109], v218 offset:32864
	ds_read_b128 v[118:121], v222 offset:112
	ds_read_b128 v[122:125], v222 offset:96
	v_add_f32_e32 v129, v90, v91
	v_add_f32_e32 v136, v86, v87
	v_lshlrev_b32_e32 v86, 16, v100
	v_and_b32_e32 v87, 0xffff0000, v100
	s_nop 0
	s_waitcnt lgkmcnt(10)
	v_mov_b32_e32 v90, v154
	v_mov_b32_e32 v91, v150
	v_pk_mul_f32 v[90:91], v[90:91], v[86:87]
	v_mov_b32_e32 v150, v155
	v_add_f32_e32 v90, 0, v90
	v_add_f32_e32 v100, v90, v91
	v_pk_mul_f32 v[90:91], v[150:151], v[86:87]
	v_lshlrev_b32_e32 v94, 16, v88
	v_add_f32_e32 v90, 0, v90
	v_add_f32_e32 v137, v90, v91
	v_lshlrev_b32_e32 v90, 16, v92
	v_and_b32_e32 v91, 0xffff0000, v92
	v_pk_fma_f32 v[90:91], v[22:23], v[90:91], v[38:39]
	v_and_b32_e32 v95, 0xffff0000, v88
	v_pk_fma_f32 v[90:91], v[26:27], v[94:95], v[90:91]
	v_lshlrev_b32_e32 v94, 16, v96
	v_and_b32_e32 v95, 0xffff0000, v96
	v_pk_fma_f32 v[90:91], v[30:31], v[94:95], v[90:91]
	v_mov_b32_e32 v94, v156
	v_pk_fma_f32 v[90:91], v[34:35], v[86:87], v[90:91]
	v_mov_b32_e32 v95, v152
	v_mul_f32_e32 v88, 0xbfb8aa3b, v90
	v_exp_f32_e32 v88, v88
	v_mul_f32_e32 v92, 0xbfb8aa3b, v91
	v_exp_f32_e32 v92, v92
	s_nop 0
	s_waitcnt lgkmcnt(8)
; __device__ __forceinline__ u32x4 pack8(const float* f) { u32x4 w; w.x = pk2(f[0], f[1]); w.y = pk2(f[2], f[3]); w.z = pk2(f[4], f[5]); w.w = pk2(f[6], f[7]); return w; }
; #define MFMA16(a, b, c) __builtin_amdgcn_mfma_f32_16x16x32_bf16((a), (b), (c), 0, 0, 0)
; __device__ void mqk_phase(const Params& p, unsigned char* smem) {
;     ...
;                 float qv[8], kv[8], vv[8];
; #pragma unroll
;                 for (int bb = 0; bb < 2; ++bb)
; #pragma unroll
;                     for (int jj = 0; jj < 4; ++jj) { float aq = 0.f, ak = 0.f, av = 0.f;
; #pragma unroll
;                         for (int ii = 0; ii < 4; ++ii) { aq += xmc[4 * bb + ii] * wqp[bb * 16 + ii * 4 + jj]; ak += xmc[4 * bb + ii] * wkp[bb * 16 + ii * 4 + jj]; av += xcur[4 * bb + ii] * wvp[bb * 16 + ii * 4 + jj]; }
;                         qv[4 * bb + jj] = aq; kv[4 * bb + jj] = ak; vv[4 * bb + jj] = av; }
;                 const u32x4 qw = pack8(qv), kw = pack8(kv), vw = pack8(vv);
;                 acc[m] = MFMA16(as_frag(qw), bq, acc[m]); acc[m] = MFMA16(as_frag(kw), bk, acc[m]); acc[m] = MFMA16(as_frag(vw), bv, acc[m]);
; #pragma unroll
;                 for (int i = 0; i < 8; ++i) kv[i] *= 0.0625f;
;                 *(u32x4*)(Q + (size_t)tk * 2048 + c0) = qw; *(u32x4*)(KX + (size_t)tk * 2048 + c0) = pack8(kv);
;             }
	v_mov_b32_e32 v126, v240
	v_add_f32_e32 v88, 1.0, v88
	v_rcp_f32_e32 v98, v88
	v_add_f32_e32 v88, 1.0, v92
	v_rcp_f32_e32 v99, v88
	v_mov_b32_e32 v127, v236
	v_pk_mul_f32 v[94:95], v[94:95], v[86:87]
	v_mov_b32_e32 v236, v241
	v_pk_mul_f32 v[90:91], v[90:91], v[98:99]
	v_mov_b32_e32 v98, v238
	v_mov_b32_e32 v99, v234
	v_pk_mul_f32 v[98:99], v[90:91], v[98:99]
	v_mov_b32_e32 v234, v239
	v_add_f32_e32 v92, 0, v98
	v_add_f32_e32 v141, v92, v99
	s_nop 0
	s_waitcnt lgkmcnt(6)
	v_mov_b32_e32 v98, v246
	v_mov_b32_e32 v99, v242
	v_pk_mul_f32 v[98:99], v[90:91], v[98:99]
	v_mov_b32_e32 v242, v247
	v_add_f32_e32 v92, 0, v98
	v_add_f32_e32 v142, v92, v99
	v_pk_mul_f32 v[98:99], v[90:91], v[234:235]
	v_pk_mul_f32 v[126:127], v[90:91], v[126:127]
	v_add_f32_e32 v92, 0, v98
	v_add_f32_e32 v143, v92, v99
	v_pk_mul_f32 v[98:99], v[90:91], v[242:243]
	v_add_f32_e32 v88, 0, v94
	v_add_f32_e32 v92, 0, v98
	v_add_f32_e32 v144, v92, v99
	v_mov_b32_e32 v98, v248
	v_mov_b32_e32 v99, v244
	v_pk_mul_f32 v[98:99], v[90:91], v[98:99]
	v_add_f32_e32 v94, 0, v126
	v_add_f32_e32 v92, 0, v98
	v_add_f32_e32 v126, v94, v127
	v_add_f32_e32 v127, v92, v99
	v_add_f32_e32 v145, v88, v95
	v_lshlrev_b32_e32 v94, 16, v101
	v_and_b32_e32 v95, 0xffff0000, v101
	s_nop 0
	s_waitcnt lgkmcnt(4)
	v_mov_b32_e32 v98, v114
	v_mov_b32_e32 v99, v110
	v_pk_mul_f32 v[98:99], v[98:99], v[94:95]
	v_mov_b32_e32 v110, v115
	v_add_f32_e32 v88, v100, v98
	v_add_f32_e32 v100, v88, v99
	v_pk_mul_f32 v[98:99], v[110:111], v[94:95]
	v_lshlrev_b32_e32 v92, 16, v93
	v_add_f32_e32 v88, v137, v98
	v_and_b32_e32 v93, 0xffff0000, v93
	v_add_f32_e32 v101, v88, v99
	v_pk_fma_f32 v[92:93], v[24:25], v[92:93], v[40:41]
	v_lshlrev_b32_e32 v88, 16, v89
	v_and_b32_e32 v89, 0xffff0000, v89
	v_pk_fma_f32 v[88:89], v[28:29], v[88:89], v[92:93]
	v_lshlrev_b32_e32 v92, 16, v97
	v_and_b32_e32 v93, 0xffff0000, v97
	v_pk_fma_f32 v[88:89], v[32:33], v[92:93], v[88:89]
	v_mov_b32_e32 v244, v249
	v_pk_fma_f32 v[88:89], v[36:37], v[94:95], v[88:89]
	v_mov_b32_e32 v152, v157
	v_mul_f32_e32 v92, 0xbfb8aa3b, v88
	v_exp_f32_e32 v93, v92
	v_mul_f32_e32 v92, 0xbfb8aa3b, v89
	v_exp_f32_e32 v97, v92
	v_mov_b32_e32 v92, v116
	v_add_f32_e32 v93, 1.0, v93
	v_rcp_f32_e32 v96, v93
	v_add_f32_e32 v93, 1.0, v97
	v_rcp_f32_e32 v97, v93
	v_mov_b32_e32 v93, v112
	v_pk_mul_f32 v[92:93], v[92:93], v[94:95]
	v_pk_mul_f32 v[86:87], v[152:153], v[86:87]
	v_pk_mul_f32 v[88:89], v[88:89], v[96:97]
	s_nop 0
	s_waitcnt lgkmcnt(2)
	v_mov_b32_e32 v96, v106
	v_mov_b32_e32 v97, v102
	v_pk_mul_f32 v[96:97], v[88:89], v[96:97]
	v_mov_b32_e32 v102, v107
	v_add_f32_e32 v96, v141, v96
	v_add_f32_e32 v106, v96, v97
	s_nop 0
	s_waitcnt lgkmcnt(0)
	v_mov_b32_e32 v96, v122
	v_mov_b32_e32 v97, v118
	v_pk_mul_f32 v[96:97], v[88:89], v[96:97]
	v_mov_b32_e32 v118, v123
	v_add_f32_e32 v96, v142, v96
	v_add_f32_e32 v110, v96, v97
	v_pk_mul_f32 v[96:97], v[88:89], v[102:103]
	v_add_f32_e32 v92, v145, v92
	v_add_f32_e32 v96, v143, v96
	v_add_f32_e32 v102, v96, v97
	v_pk_mul_f32 v[96:97], v[88:89], v[118:119]
	v_mov_b32_e32 v99, v104
	v_add_f32_e32 v96, v144, v96
	v_add_f32_e32 v107, v96, v97
	v_mov_b32_e32 v96, v124
	v_mov_b32_e32 v97, v120
	v_pk_mul_f32 v[96:97], v[88:89], v[96:97]
	v_add_f32_e32 v86, 0, v86
	v_add_f32_e32 v96, v127, v96
	v_add_f32_e32 v96, v96, v97
	v_add_f32_e32 v97, v92, v93
	v_pk_mul_f32 v[92:93], v[90:91], v[236:237]
	v_pk_mul_f32 v[90:91], v[90:91], v[244:245]
	v_add_f32_e32 v92, 0, v92
	v_add_f32_e32 v90, 0, v90
	v_mov_b32_e32 v104, v109
	v_add_f32_e32 v92, v92, v93
	v_add_f32_e32 v90, v90, v91
	v_add_f32_e32 v91, v86, v87
	v_pk_mul_f32 v[86:87], v[88:89], v[104:105]
	v_mov_b32_e32 v98, v108
	v_add_f32_e32 v86, v92, v86
	v_mov_b32_e32 v120, v125
	v_pk_mul_f32 v[98:99], v[88:89], v[98:99]
	v_add_f32_e32 v92, v86, v87
	v_pk_mul_f32 v[86:87], v[88:89], v[120:121]
	v_add_f32_e32 v98, v126, v98
	v_add_f32_e32 v86, v90, v86
	v_mov_b32_e32 v112, v117
	v_add_f32_e32 v98, v98, v99
	v_add_f32_e32 v99, v86, v87
	v_pk_mul_f32 v[86:87], v[112:113], v[94:95]
	v_mul_f32_e32 v108, 0x3d800000, v96
	v_add_f32_e32 v86, v91, v86
	v_add_f32_e32 v94, v86, v87
	v_cvt_pk_bf16_f32 v86, v131, v138
	v_cvt_pk_bf16_f32 v87, v135, v129
	v_cvt_pk_bf16_f32 v88, v106, v102
	v_cvt_pk_bf16_f32 v89, v98, v92
	v_cvt_pk_bf16_f32 v90, v132, v134
	v_cvt_pk_bf16_f32 v91, v139, v133
	v_cvt_pk_bf16_f32 v92, v110, v107
	v_cvt_pk_bf16_f32 v93, v96, v99
	v_cvt_pk_bf16_f32 v102, v128, v130
	v_cvt_pk_bf16_f32 v103, v140, v136
	v_cvt_pk_bf16_f32 v104, v100, v101
	v_cvt_pk_bf16_f32 v105, v97, v94
	v_mul_f32_e32 v97, 0x3d800000, v132
	v_mul_f32_e32 v98, 0x3d800000, v134
	v_mul_f32_e32 v99, 0x3d800000, v99
	v_lshl_add_u64 v[94:95], v[216:217], 0, v[206:207]
	v_mul_f32_e32 v100, 0x3d800000, v139
	v_mul_f32_e32 v101, 0x3d800000, v133
	v_mul_f32_e32 v106, 0x3d800000, v110
	v_mul_f32_e32 v107, 0x3d800000, v107
	global_store_dwordx4 v[94:95], v[86:89], off
	v_cvt_pk_bf16_f32 v94, v97, v98
	v_cvt_pk_bf16_f32 v95, v100, v101
	v_cvt_pk_bf16_f32 v96, v106, v107
	v_cvt_pk_bf16_f32 v97, v108, v99
	v_lshl_add_u64 v[98:99], v[214:215], 0, v[206:207]
	global_store_dwordx4 v[98:99], v[94:97], off
	ds_read_b128 v[118:121], v218
	ds_read_b128 v[114:117], v218 offset:16
	ds_read_b128 v[138:141], v218 offset:32768
	ds_read_b128 v[134:137], v218 offset:32784
	ds_read_b128 v[130:133], v222
	ds_read_b128 v[126:129], v222 offset:16
	ds_read_b128 v[110:113], v218 offset:32
	ds_read_b128 v[106:109], v218 offset:48
	v_mfma_f32_16x16x32_bf16 v[66:69], v[86:89], v[18:21], v[66:69]
	v_lshl_add_u64 v[86:87], v[224:225], 0, v[190:191]
	v_lshl_add_u64 v[88:89], v[224:225], 0, v[192:193]
	v_lshl_add_u64 v[98:99], v[224:225], 0, v[196:197]
	v_mfma_f32_16x16x32_bf16 v[66:69], v[90:93], v[14:17], v[66:69]
	global_load_dwordx4 v[94:97], v[86:87], off
	global_load_dwordx4 v[90:93], v[88:89], off
	v_lshl_add_u64 v[86:87], v[224:225], 0, v[194:195]
	global_load_dwordx4 v[86:89], v[86:87], off
	s_nop 0
	global_load_dwordx4 v[98:101], v[98:99], off
	s_nop 0
	ds_read_b128 v[146:149], v218 offset:32816
	ds_read_b128 v[150:153], v218 offset:32800
	ds_read_b128 v[122:125], v222 offset:48
	ds_read_b128 v[142:145], v222 offset:32
	s_waitcnt vmcnt(7)
; __device__ __forceinline__ void unpack8(u32x4 w, float* f) { f[0] = bflo(w.x); f[1] = bfhi(w.x); f[2] = bflo(w.y); f[3] = bfhi(w.y); f[4] = bflo(w.z); f[5] = bfhi(w.z); f[6] = bflo(w.w); f[7] = bfhi(w.w); }
; __device__ __forceinline__ u32x4 pack8(const float* f) { u32x4 w; w.x = pk2(f[0], f[1]); w.y = pk2(f[2], f[3]); w.z = pk2(f[4], f[5]); w.w = pk2(f[6], f[7]); return w; }
; #define MFMA16(a, b, c) __builtin_amdgcn_mfma_f32_16x16x32_bf16((a), (b), (c), 0, 0, 0)
; __device__ __forceinline__ float fsig0(float x) { return __builtin_amdgcn_rcpf(1.0f + __expf(-x)); }
; __device__ void mqk_phase(const Params& p, unsigned char* smem) {
;     ...
;                 for (int j = 0; j < 4; ++j) { float xv[8]; unpack8(xraw[j], xv);
; #pragma unroll
;                     for (int i = 0; i < 8; ++i) { xmc[i] += cw[j][i] * xv[i]; if (j == 3) xcur[i] = xv[i]; } }
;                 if (m < 3) {
; #pragma unroll
;                     for (int j = 0; j < 4; ++j) xraw[j] = xnx[j]; }
; #pragma unroll
;                 for (int i = 0; i < 8; ++i) xmc[i] = xmc[i] * fsig0(xmc[i]);
;                 float qv[8], kv[8], vv[8];
; #pragma unroll
;                 for (int bb = 0; bb < 2; ++bb)
; #pragma unroll
;                     for (int jj = 0; jj < 4; ++jj) { float aq = 0.f, ak = 0.f, av = 0.f;
; #pragma unroll
;                         for (int ii = 0; ii < 4; ++ii) { aq += xmc[4 * bb + ii] * wqp[bb * 16 + ii * 4 + jj]; ak += xmc[4 * bb + ii] * wkp[bb * 16 + ii * 4 + jj]; av += xcur[4 * bb + ii] * wvp[bb * 16 + ii * 4 + jj]; }
;                         qv[4 * bb + jj] = aq; kv[4 * bb + jj] = ak; vv[4 * bb + jj] = av; }
;                 const u32x4 qw = pack8(qv), kw = pack8(kv), vw = pack8(vv);
;                 acc[m] = MFMA16(as_frag(qw), bq, acc[m]); acc[m] = MFMA16(as_frag(kw), bk, acc[m]); acc[m] = MFMA16(as_frag(vw), bv, acc[m]);
	v_lshlrev_b32_e32 v226, 16, v82
	v_and_b32_e32 v227, 0xffff0000, v82
	v_mfma_f32_16x16x32_bf16 v[66:69], v[102:105], v[10:13], v[66:69]
	s_nop 0
	s_waitcnt lgkmcnt(11)
	v_mov_b32_e32 v154, v118
	s_nop 0
	s_waitcnt lgkmcnt(10)
	v_mov_b32_e32 v155, v114
	v_pk_mul_f32 v[154:155], v[154:155], v[226:227]
	v_mov_b32_e32 v114, v119
	v_add_f32_e32 v82, 0, v154
	v_pk_mul_f32 v[114:115], v[114:115], v[226:227]
	v_add_f32_e32 v156, v82, v155
	v_add_f32_e32 v82, 0, v114
	v_add_f32_e32 v157, v82, v115
	v_lshlrev_b32_e32 v114, 16, v78
	v_and_b32_e32 v115, 0xffff0000, v78
	v_pk_fma_f32 v[114:115], v[46:47], v[114:115], v[58:59]
	v_lshlrev_b32_e32 v118, 16, v74
	v_and_b32_e32 v119, 0xffff0000, v74
	v_pk_fma_f32 v[114:115], v[50:51], v[118:119], v[114:115]
	v_lshlrev_b32_e32 v118, 16, v70
	v_and_b32_e32 v119, 0xffff0000, v70
	v_pk_fma_f32 v[114:115], v[54:55], v[118:119], v[114:115]
	v_mov_b32_e32 v119, v116
	v_pk_fma_f32 v[114:115], v[42:43], v[226:227], v[114:115]
	v_mov_b32_e32 v118, v120
	v_mul_f32_e32 v70, 0xbfb8aa3b, v114
	v_exp_f32_e32 v70, v70
	v_mul_f32_e32 v74, 0xbfb8aa3b, v115
	v_exp_f32_e32 v74, v74
	v_pk_mul_f32 v[118:119], v[118:119], v[226:227]
	v_add_f32_e32 v70, 1.0, v70
	v_rcp_f32_e32 v154, v70
	v_add_f32_e32 v70, 1.0, v74
	v_rcp_f32_e32 v155, v70
	v_add_f32_e32 v70, 0, v118
	v_lshlrev_b32_e32 v82, 16, v83
	v_and_b32_e32 v83, 0xffff0000, v83
	v_pk_mul_f32 v[114:115], v[114:115], v[154:155]
	s_nop 0
	s_waitcnt lgkmcnt(9)
	v_mov_b32_e32 v154, v138
	s_nop 0
	s_waitcnt lgkmcnt(8)
	v_mov_b32_e32 v155, v134
	v_pk_mul_f32 v[154:155], v[114:115], v[154:155]
	v_mov_b32_e32 v134, v139
	v_add_f32_e32 v74, 0, v154
	v_add_f32_e32 v116, v74, v155
	s_nop 0
	s_waitcnt lgkmcnt(7)
	v_mov_b32_e32 v154, v130
	s_nop 0
	s_waitcnt lgkmcnt(6)
	v_mov_b32_e32 v155, v126
	v_pk_mul_f32 v[154:155], v[114:115], v[154:155]
	v_pk_mul_f32 v[134:135], v[114:115], v[134:135]
	v_add_f32_e32 v74, 0, v154
	v_mov_b32_e32 v126, v131
	v_add_f32_e32 v120, v74, v155
	v_add_f32_e32 v74, 0, v134
	v_pk_mul_f32 v[126:127], v[114:115], v[126:127]
	v_add_f32_e32 v134, v74, v135
	v_add_f32_e32 v74, 0, v126
	v_add_f32_e32 v135, v74, v127
	v_mov_b32_e32 v127, v128
	v_add_f32_e32 v128, v70, v119
	s_nop 0
	s_waitcnt lgkmcnt(5)
	v_mov_b32_e32 v118, v110
	s_nop 0
	s_waitcnt lgkmcnt(4)
	v_mov_b32_e32 v119, v106
	v_pk_mul_f32 v[118:119], v[118:119], v[82:83]
	v_mov_b32_e32 v106, v111
	v_add_f32_e32 v70, v156, v118
	v_pk_mul_f32 v[106:107], v[106:107], v[82:83]
	v_mov_b32_e32 v126, v132
	v_mov_b32_e32 v130, v140
	v_mov_b32_e32 v131, v136
	v_add_f32_e32 v132, v70, v119
	v_add_f32_e32 v70, v157, v106
	ds_read_b128 v[154:157], v218 offset:80
	ds_read_b128 v[158:161], v218 offset:64
	v_pk_mul_f32 v[130:131], v[114:115], v[130:131]
	v_pk_mul_f32 v[126:127], v[114:115], v[126:127]
	v_add_f32_e32 v78, 0, v130
	v_add_f32_e32 v74, 0, v126
	v_add_f32_e32 v126, v78, v131
	v_lshlrev_b32_e32 v78, 16, v79
	v_and_b32_e32 v79, 0xffff0000, v79
	v_add_f32_e32 v127, v74, v127
	v_pk_fma_f32 v[78:79], v[48:49], v[78:79], v[60:61]
	v_lshlrev_b32_e32 v74, 16, v75
	v_and_b32_e32 v75, 0xffff0000, v75
	v_add_f32_e32 v138, v70, v107
	v_pk_fma_f32 v[74:75], v[52:53], v[74:75], v[78:79]
	v_lshlrev_b32_e32 v70, 16, v71
	v_and_b32_e32 v71, 0xffff0000, v71
	v_pk_fma_f32 v[70:71], v[56:57], v[70:71], v[74:75]
	ds_read_b128 v[234:237], v218 offset:32848
	ds_read_b128 v[238:241], v218 offset:32832
	v_pk_fma_f32 v[70:71], v[44:45], v[82:83], v[70:71]
	ds_read_b128 v[242:245], v222 offset:80
	ds_read_b128 v[246:249], v222 offset:64
	v_mul_f32_e32 v74, 0xbfb8aa3b, v70
	v_exp_f32_e32 v75, v74
	v_mul_f32_e32 v74, 0xbfb8aa3b, v71
	v_exp_f32_e32 v79, v74
	v_mov_b32_e32 v74, v112
	v_add_f32_e32 v75, 1.0, v75
	v_rcp_f32_e32 v78, v75
	v_add_f32_e32 v75, 1.0, v79
	v_rcp_f32_e32 v79, v75
	v_mov_b32_e32 v75, v108
	v_pk_mul_f32 v[74:75], v[74:75], v[82:83]
	v_mov_b32_e32 v136, v141
	v_pk_mul_f32 v[70:71], v[70:71], v[78:79]
	s_nop 0
	s_waitcnt lgkmcnt(8)
	v_mov_b32_e32 v78, v150
	v_mov_b32_e32 v79, v146
	v_pk_mul_f32 v[78:79], v[70:71], v[78:79]
	v_mov_b32_e32 v146, v151
	v_add_f32_e32 v78, v116, v78
	v_add_f32_e32 v139, v78, v79
	s_nop 0
	s_waitcnt lgkmcnt(6)
	v_mov_b32_e32 v78, v142
	v_mov_b32_e32 v79, v122
	v_pk_mul_f32 v[78:79], v[70:71], v[78:79]
	v_mov_b32_e32 v122, v143
	v_add_f32_e32 v78, v120, v78
	v_add_f32_e32 v140, v78, v79
	v_pk_mul_f32 v[78:79], v[70:71], v[146:147]
	v_add_f32_e32 v74, v128, v74
	v_add_f32_e32 v78, v134, v78
	v_add_f32_e32 v134, v78, v79
	v_pk_mul_f32 v[78:79], v[70:71], v[122:123]
	v_mov_b32_e32 v128, v133
	v_add_f32_e32 v78, v135, v78
	v_add_f32_e32 v135, v78, v79
	v_mov_b32_e32 v78, v144
	v_mov_b32_e32 v79, v124
	v_pk_mul_f32 v[78:79], v[70:71], v[78:79]
	v_add_f32_e32 v144, v74, v75
	v_pk_mul_f32 v[74:75], v[114:115], v[136:137]
	v_add_f32_e32 v78, v127, v78
	v_add_f32_e32 v74, 0, v74
	v_add_f32_e32 v143, v78, v79
	v_add_f32_e32 v78, v74, v75
	v_pk_mul_f32 v[74:75], v[114:115], v[128:129]
	v_mov_b32_e32 v116, v121
	v_add_f32_e32 v74, 0, v74
	v_add_f32_e32 v79, v74, v75
	v_pk_mul_f32 v[74:75], v[116:117], v[226:227]
	ds_read_b128 v[114:117], v218 offset:112
	ds_read_b128 v[118:121], v218 offset:96
	v_mov_b32_e32 v106, v152
	v_mov_b32_e32 v107, v148
	v_pk_mul_f32 v[106:107], v[70:71], v[106:107]
	v_add_f32_e32 v74, 0, v74
	v_add_f32_e32 v106, v126, v106
	v_mov_b32_e32 v148, v153
	v_mov_b32_e32 v124, v145
	v_add_f32_e32 v142, v106, v107
	v_add_f32_e32 v106, v74, v75
	v_pk_mul_f32 v[74:75], v[70:71], v[148:149]
	v_pk_mul_f32 v[70:71], v[70:71], v[124:125]
	v_mov_b32_e32 v108, v113
	v_add_f32_e32 v70, v79, v70
	v_add_f32_e32 v136, v70, v71
	v_pk_mul_f32 v[70:71], v[108:109], v[82:83]
	v_add_f32_e32 v74, v78, v74
	v_add_f32_e32 v70, v106, v70
	ds_read_b128 v[106:109], v218 offset:32880
	ds_read_b128 v[110:113], v218 offset:32864
	ds_read_b128 v[122:125], v222 offset:112
	ds_read_b128 v[126:129], v222 offset:96
	v_add_f32_e32 v133, v74, v75
	v_add_f32_e32 v137, v70, v71
	v_lshlrev_b32_e32 v70, 16, v84
	v_and_b32_e32 v71, 0xffff0000, v84
	s_nop 0
	s_waitcnt lgkmcnt(10)
; __device__ __forceinline__ u32x4 pack8(const float* f) { u32x4 w; w.x = pk2(f[0], f[1]); w.y = pk2(f[2], f[3]); w.z = pk2(f[4], f[5]); w.w = pk2(f[6], f[7]); return w; }
; #define MFMA16(a, b, c) __builtin_amdgcn_mfma_f32_16x16x32_bf16((a), (b), (c), 0, 0, 0)
; __device__ __forceinline__ float fsig0(float x) { return __builtin_amdgcn_rcpf(1.0f + __expf(-x)); }
; __device__ void mqk_phase(const Params& p, unsigned char* smem) {
;     ...
;                 for (int i = 0; i < 8; ++i) xmc[i] = xmc[i] * fsig0(xmc[i]);
;                 float qv[8], kv[8], vv[8];
; #pragma unroll
;                 for (int bb = 0; bb < 2; ++bb)
; #pragma unroll
;                     for (int jj = 0; jj < 4; ++jj) { float aq = 0.f, ak = 0.f, av = 0.f;
; #pragma unroll
;                         for (int ii = 0; ii < 4; ++ii) { aq += xmc[4 * bb + ii] * wqp[bb * 16 + ii * 4 + jj]; ak += xmc[4 * bb + ii] * wkp[bb * 16 + ii * 4 + jj]; av += xcur[4 * bb + ii] * wvp[bb * 16 + ii * 4 + jj]; }
;                         qv[4 * bb + jj] = aq; kv[4 * bb + jj] = ak; vv[4 * bb + jj] = av; }
;                 const u32x4 qw = pack8(qv), kw = pack8(kv), vw = pack8(vv);
;                 acc[m] = MFMA16(as_frag(qw), bq, acc[m]); acc[m] = MFMA16(as_frag(kw), bk, acc[m]); acc[m] = MFMA16(as_frag(vw), bv, acc[m]);
; #pragma unroll
;                 for (int i = 0; i < 8; ++i) kv[i] *= 0.0625f;
;                 *(u32x4*)(Q + (size_t)tk * 2048 + c0) = qw; *(u32x4*)(KX + (size_t)tk * 2048 + c0) = pack8(kv);
;             }
	v_mov_b32_e32 v74, v158
	v_mov_b32_e32 v75, v154
	v_pk_mul_f32 v[74:75], v[74:75], v[70:71]
	v_mov_b32_e32 v154, v159
	v_add_f32_e32 v74, 0, v74
	v_add_f32_e32 v84, v74, v75
	v_pk_mul_f32 v[74:75], v[154:155], v[70:71]
	v_lshlrev_b32_e32 v78, 16, v76
	v_add_f32_e32 v74, 0, v74
	v_add_f32_e32 v141, v74, v75
	v_lshlrev_b32_e32 v74, 16, v80
	v_and_b32_e32 v75, 0xffff0000, v80
	v_pk_fma_f32 v[74:75], v[22:23], v[74:75], v[38:39]
	v_and_b32_e32 v79, 0xffff0000, v76
	v_pk_fma_f32 v[74:75], v[26:27], v[78:79], v[74:75]
	v_lshlrev_b32_e32 v78, 16, v72
	v_and_b32_e32 v79, 0xffff0000, v72
	v_pk_fma_f32 v[74:75], v[30:31], v[78:79], v[74:75]
	v_mov_b32_e32 v78, v160
	v_pk_fma_f32 v[74:75], v[34:35], v[70:71], v[74:75]
	v_mov_b32_e32 v79, v156
	v_mul_f32_e32 v72, 0xbfb8aa3b, v74
	v_exp_f32_e32 v72, v72
	v_mul_f32_e32 v76, 0xbfb8aa3b, v75
	v_exp_f32_e32 v76, v76
	s_nop 0
	s_waitcnt lgkmcnt(8)
	v_mov_b32_e32 v130, v240
	v_add_f32_e32 v72, 1.0, v72
	v_rcp_f32_e32 v82, v72
	v_add_f32_e32 v72, 1.0, v76
	v_rcp_f32_e32 v83, v72
	v_mov_b32_e32 v131, v236
	v_pk_mul_f32 v[78:79], v[78:79], v[70:71]
	v_lshlrev_b32_e32 v80, 16, v81
	v_pk_mul_f32 v[74:75], v[74:75], v[82:83]
	v_mov_b32_e32 v82, v238
	v_mov_b32_e32 v83, v234
	v_pk_mul_f32 v[82:83], v[74:75], v[82:83]
	v_mov_b32_e32 v234, v239
	v_add_f32_e32 v76, 0, v82
	v_add_f32_e32 v145, v76, v83
	s_nop 0
	s_waitcnt lgkmcnt(6)
	v_mov_b32_e32 v82, v246
	v_mov_b32_e32 v83, v242
	v_pk_mul_f32 v[82:83], v[74:75], v[82:83]
	v_mov_b32_e32 v242, v247
	v_add_f32_e32 v76, 0, v82
	v_add_f32_e32 v146, v76, v83
	v_pk_mul_f32 v[82:83], v[74:75], v[234:235]
	v_pk_mul_f32 v[130:131], v[74:75], v[130:131]
	v_add_f32_e32 v76, 0, v82
	v_add_f32_e32 v147, v76, v83
	v_pk_mul_f32 v[82:83], v[74:75], v[242:243]
	v_add_f32_e32 v72, 0, v78
	v_add_f32_e32 v76, 0, v82
	v_add_f32_e32 v148, v76, v83
	v_mov_b32_e32 v82, v248
	v_mov_b32_e32 v83, v244
	v_pk_mul_f32 v[82:83], v[74:75], v[82:83]
	v_add_f32_e32 v78, 0, v130
	v_add_f32_e32 v76, 0, v82
	v_add_f32_e32 v130, v78, v131
	v_add_f32_e32 v131, v76, v83
	v_add_f32_e32 v149, v72, v79
	v_lshlrev_b32_e32 v78, 16, v85
	v_and_b32_e32 v79, 0xffff0000, v85
	s_nop 0
	s_waitcnt lgkmcnt(4)
	v_mov_b32_e32 v82, v118
	v_mov_b32_e32 v83, v114
	v_pk_mul_f32 v[82:83], v[82:83], v[78:79]
	v_mov_b32_e32 v114, v119
	v_add_f32_e32 v72, v84, v82
	v_add_f32_e32 v84, v72, v83
	v_pk_mul_f32 v[82:83], v[114:115], v[78:79]
	v_and_b32_e32 v81, 0xffff0000, v81
	v_add_f32_e32 v72, v141, v82
	v_pk_fma_f32 v[80:81], v[24:25], v[80:81], v[40:41]
	v_lshlrev_b32_e32 v76, 16, v77
	v_and_b32_e32 v77, 0xffff0000, v77
	v_add_f32_e32 v85, v72, v83
	v_pk_fma_f32 v[76:77], v[28:29], v[76:77], v[80:81]
	v_lshlrev_b32_e32 v72, 16, v73
	v_and_b32_e32 v73, 0xffff0000, v73
	v_pk_fma_f32 v[72:73], v[32:33], v[72:73], v[76:77]
	v_mov_b32_e32 v236, v241
	v_pk_fma_f32 v[72:73], v[36:37], v[78:79], v[72:73]
	v_mov_b32_e32 v244, v249
	v_mul_f32_e32 v76, 0xbfb8aa3b, v72
	v_exp_f32_e32 v77, v76
	v_mul_f32_e32 v76, 0xbfb8aa3b, v73
	v_exp_f32_e32 v81, v76
	v_mov_b32_e32 v76, v120
	v_add_f32_e32 v77, 1.0, v77
	v_rcp_f32_e32 v80, v77
	v_add_f32_e32 v77, 1.0, v81
	v_rcp_f32_e32 v81, v77
	v_mov_b32_e32 v77, v116
	v_pk_mul_f32 v[76:77], v[76:77], v[78:79]
	v_mov_b32_e32 v156, v161
	v_pk_mul_f32 v[72:73], v[72:73], v[80:81]
	s_nop 0
	s_waitcnt lgkmcnt(2)
	v_mov_b32_e32 v80, v110
	v_mov_b32_e32 v81, v106
	v_pk_mul_f32 v[80:81], v[72:73], v[80:81]
	v_mov_b32_e32 v106, v111
	v_add_f32_e32 v80, v145, v80
	v_add_f32_e32 v110, v80, v81
	s_nop 0
	s_waitcnt lgkmcnt(0)
	v_mov_b32_e32 v80, v126
	v_mov_b32_e32 v81, v122
	v_pk_mul_f32 v[80:81], v[72:73], v[80:81]
	v_mov_b32_e32 v122, v127
	v_add_f32_e32 v80, v146, v80
	v_add_f32_e32 v114, v80, v81
	v_pk_mul_f32 v[80:81], v[72:73], v[106:107]
	v_add_f32_e32 v76, v149, v76
	v_add_f32_e32 v80, v147, v80
	v_add_f32_e32 v106, v80, v81
	v_pk_mul_f32 v[80:81], v[72:73], v[122:123]
	v_pk_mul_f32 v[70:71], v[156:157], v[70:71]
	v_add_f32_e32 v80, v148, v80
	v_add_f32_e32 v111, v80, v81
	v_mov_b32_e32 v80, v128
	v_mov_b32_e32 v81, v124
	v_pk_mul_f32 v[80:81], v[72:73], v[80:81]
	v_mov_b32_e32 v83, v108
	v_add_f32_e32 v80, v131, v80
	v_add_f32_e32 v80, v80, v81
	v_add_f32_e32 v81, v76, v77
	v_pk_mul_f32 v[76:77], v[74:75], v[236:237]
	v_pk_mul_f32 v[74:75], v[74:75], v[244:245]
	v_add_f32_e32 v76, 0, v76
	v_add_f32_e32 v74, 0, v74
	v_add_f32_e32 v70, 0, v70
	v_mov_b32_e32 v108, v113
	v_add_f32_e32 v76, v76, v77
	v_add_f32_e32 v74, v74, v75
	v_add_f32_e32 v75, v70, v71
	v_pk_mul_f32 v[70:71], v[72:73], v[108:109]
	v_mov_b32_e32 v82, v112
	v_add_f32_e32 v70, v76, v70
	v_mov_b32_e32 v124, v129
	v_pk_mul_f32 v[82:83], v[72:73], v[82:83]
	v_add_f32_e32 v76, v70, v71
	v_pk_mul_f32 v[70:71], v[72:73], v[124:125]
	v_add_f32_e32 v82, v130, v82
	v_add_f32_e32 v70, v74, v70
	v_mov_b32_e32 v116, v121
	v_add_f32_e32 v82, v82, v83
	v_add_f32_e32 v83, v70, v71
	v_pk_mul_f32 v[70:71], v[116:117], v[78:79]
	v_mul_f32_e32 v112, 0x3d800000, v80
	v_add_f32_e32 v70, v75, v70
	v_add_f32_e32 v78, v70, v71
	v_cvt_pk_bf16_f32 v70, v139, v134
	v_cvt_pk_bf16_f32 v71, v142, v133
	v_cvt_pk_bf16_f32 v72, v110, v106
	v_cvt_pk_bf16_f32 v73, v82, v76
	v_cvt_pk_bf16_f32 v74, v140, v135
	v_cvt_pk_bf16_f32 v75, v143, v136
	v_cvt_pk_bf16_f32 v76, v114, v111
	v_cvt_pk_bf16_f32 v77, v80, v83
	v_cvt_pk_bf16_f32 v106, v132, v138
	v_cvt_pk_bf16_f32 v107, v144, v137
	v_cvt_pk_bf16_f32 v108, v84, v85
	v_cvt_pk_bf16_f32 v109, v81, v78
	v_mul_f32_e32 v81, 0x3d800000, v140
	v_mul_f32_e32 v82, 0x3d800000, v135
	v_mul_f32_e32 v83, 0x3d800000, v83
	v_lshl_add_u64 v[78:79], v[216:217], 0, v[208:209]
	v_mul_f32_e32 v84, 0x3d800000, v143
	v_mul_f32_e32 v85, 0x3d800000, v136
	v_mul_f32_e32 v110, 0x3d800000, v114
	v_mul_f32_e32 v111, 0x3d800000, v111
	global_store_dwordx4 v[78:79], v[70:73], off
	v_cvt_pk_bf16_f32 v78, v81, v82
	v_cvt_pk_bf16_f32 v79, v84, v85
	v_cvt_pk_bf16_f32 v80, v110, v111
	v_cvt_pk_bf16_f32 v81, v112, v83
	v_lshl_add_u64 v[82:83], v[214:215], 0, v[208:209]
	global_store_dwordx4 v[82:83], v[78:81], off
	ds_read_b128 v[118:121], v218
	ds_read_b128 v[114:117], v218 offset:16
	ds_read_b128 v[138:141], v218 offset:32768
	ds_read_b128 v[134:137], v218 offset:32784
	ds_read_b128 v[130:133], v222
	ds_read_b128 v[126:129], v222 offset:16
	ds_read_b128 v[110:113], v218 offset:32
	ds_read_b128 v[102:105], v218 offset:48
	v_mfma_f32_16x16x32_bf16 v[62:65], v[70:73], v[18:21], v[62:65]
	v_lshl_add_u64 v[70:71], v[224:225], 0, v[198:199]
	v_lshl_add_u64 v[72:73], v[224:225], 0, v[200:201]
	v_lshl_add_u64 v[82:83], v[224:225], 0, v[204:205]
	v_mfma_f32_16x16x32_bf16 v[62:65], v[74:77], v[14:17], v[62:65]
	global_load_dwordx4 v[78:81], v[70:71], off
	global_load_dwordx4 v[74:77], v[72:73], off
	v_lshl_add_u64 v[70:71], v[224:225], 0, v[202:203]
	global_load_dwordx4 v[70:73], v[70:71], off
	s_nop 0
	global_load_dwordx4 v[82:85], v[82:83], off
	s_nop 0
	ds_read_b128 v[146:149], v218 offset:32816
	ds_read_b128 v[150:153], v218 offset:32800
	ds_read_b128 v[122:125], v222 offset:48
	ds_read_b128 v[142:145], v222 offset:32
	s_waitcnt vmcnt(6)
; __device__ __forceinline__ void unpack8(u32x4 w, float* f) { f[0] = bflo(w.x); f[1] = bfhi(w.x); f[2] = bflo(w.y); f[3] = bfhi(w.y); f[4] = bflo(w.z); f[5] = bfhi(w.z); f[6] = bflo(w.w); f[7] = bfhi(w.w); }
; __device__ __forceinline__ u32x4 pack8(const float* f) { u32x4 w; w.x = pk2(f[0], f[1]); w.y = pk2(f[2], f[3]); w.z = pk2(f[4], f[5]); w.w = pk2(f[6], f[7]); return w; }
; #define MFMA16(a, b, c) __builtin_amdgcn_mfma_f32_16x16x32_bf16((a), (b), (c), 0, 0, 0)
; __device__ __forceinline__ float fsig0(float x) { return __builtin_amdgcn_rcpf(1.0f + __expf(-x)); }
; __device__ void mqk_phase(const Params& p, unsigned char* smem) {
;     ...
;                 for (int j = 0; j < 4; ++j) { float xv[8]; unpack8(xraw[j], xv);
; #pragma unroll
;                     for (int i = 0; i < 8; ++i) { xmc[i] += cw[j][i] * xv[i]; if (j == 3) xcur[i] = xv[i]; } }
;                 if (m < 3) {
; #pragma unroll
;                     for (int j = 0; j < 4; ++j) xraw[j] = xnx[j]; }
; #pragma unroll
;                 for (int i = 0; i < 8; ++i) xmc[i] = xmc[i] * fsig0(xmc[i]);
;                 float qv[8], kv[8], vv[8];
; #pragma unroll
;                 for (int bb = 0; bb < 2; ++bb)
; #pragma unroll
;                     for (int jj = 0; jj < 4; ++jj) { float aq = 0.f, ak = 0.f, av = 0.f;
; #pragma unroll
;                         for (int ii = 0; ii < 4; ++ii) { aq += xmc[4 * bb + ii] * wqp[bb * 16 + ii * 4 + jj]; ak += xmc[4 * bb + ii] * wkp[bb * 16 + ii * 4 + jj]; av += xcur[4 * bb + ii] * wvp[bb * 16 + ii * 4 + jj]; }
;                         qv[4 * bb + jj] = aq; kv[4 * bb + jj] = ak; vv[4 * bb + jj] = av; }
;                 const u32x4 qw = pack8(qv), kw = pack8(kv), vw = pack8(vv);
;                 acc[m] = MFMA16(as_frag(qw), bq, acc[m]); acc[m] = MFMA16(as_frag(kw), bk, acc[m]); acc[m] = MFMA16(as_frag(vw), bv, acc[m]);
	v_lshlrev_b32_e32 v224, 16, v98
	v_and_b32_e32 v225, 0xffff0000, v98
	v_mfma_f32_16x16x32_bf16 v[62:65], v[106:109], v[10:13], v[62:65]
	s_nop 0
	s_waitcnt lgkmcnt(11)
	v_mov_b32_e32 v154, v118
	s_nop 0
	s_waitcnt lgkmcnt(10)
	v_mov_b32_e32 v155, v114
	v_pk_mul_f32 v[154:155], v[154:155], v[224:225]
	v_mov_b32_e32 v114, v119
	v_add_f32_e32 v98, 0, v154
	v_pk_mul_f32 v[114:115], v[114:115], v[224:225]
	v_add_f32_e32 v156, v98, v155
	v_add_f32_e32 v98, 0, v114
	v_add_f32_e32 v157, v98, v115
	v_lshlrev_b32_e32 v114, 16, v94
	v_and_b32_e32 v115, 0xffff0000, v94
	v_pk_fma_f32 v[114:115], v[46:47], v[114:115], v[58:59]
	v_lshlrev_b32_e32 v118, 16, v90
	v_and_b32_e32 v119, 0xffff0000, v90
	v_pk_fma_f32 v[114:115], v[50:51], v[118:119], v[114:115]
	v_lshlrev_b32_e32 v118, 16, v86
	v_and_b32_e32 v119, 0xffff0000, v86
	v_pk_fma_f32 v[114:115], v[54:55], v[118:119], v[114:115]
	v_mov_b32_e32 v119, v116
	v_pk_fma_f32 v[114:115], v[42:43], v[224:225], v[114:115]
	v_mov_b32_e32 v118, v120
	v_mul_f32_e32 v86, 0xbfb8aa3b, v114
	v_exp_f32_e32 v86, v86
	v_mul_f32_e32 v90, 0xbfb8aa3b, v115
	v_exp_f32_e32 v90, v90
	v_pk_mul_f32 v[118:119], v[118:119], v[224:225]
	v_add_f32_e32 v86, 1.0, v86
	v_rcp_f32_e32 v154, v86
	v_add_f32_e32 v86, 1.0, v90
	v_rcp_f32_e32 v155, v86
	v_add_f32_e32 v86, 0, v118
	v_lshlrev_b32_e32 v98, 16, v99
	v_and_b32_e32 v99, 0xffff0000, v99
	v_pk_mul_f32 v[114:115], v[114:115], v[154:155]
	s_nop 0
	s_waitcnt lgkmcnt(9)
	v_mov_b32_e32 v154, v138
	s_nop 0
	s_waitcnt lgkmcnt(8)
	v_mov_b32_e32 v155, v134
	v_pk_mul_f32 v[154:155], v[114:115], v[154:155]
	v_mov_b32_e32 v134, v139
	v_add_f32_e32 v90, 0, v154
	v_add_f32_e32 v116, v90, v155
	s_nop 0
	s_waitcnt lgkmcnt(7)
	v_mov_b32_e32 v154, v130
	s_nop 0
	s_waitcnt lgkmcnt(6)
	v_mov_b32_e32 v155, v126
	v_pk_mul_f32 v[154:155], v[114:115], v[154:155]
	v_pk_mul_f32 v[134:135], v[114:115], v[134:135]
	v_add_f32_e32 v90, 0, v154
	v_mov_b32_e32 v126, v131
	v_add_f32_e32 v120, v90, v155
	v_add_f32_e32 v90, 0, v134
	v_pk_mul_f32 v[126:127], v[114:115], v[126:127]
	v_add_f32_e32 v134, v90, v135
	v_add_f32_e32 v90, 0, v126
	v_add_f32_e32 v135, v90, v127
	v_mov_b32_e32 v127, v128
	v_add_f32_e32 v128, v86, v119
	s_nop 0
	s_waitcnt lgkmcnt(5)
	v_mov_b32_e32 v118, v110
	s_nop 0
	s_waitcnt lgkmcnt(4)
	v_mov_b32_e32 v119, v102
	v_pk_mul_f32 v[118:119], v[118:119], v[98:99]
	v_mov_b32_e32 v102, v111
	v_add_f32_e32 v86, v156, v118
	v_pk_mul_f32 v[102:103], v[102:103], v[98:99]
	v_mov_b32_e32 v126, v132
	v_mov_b32_e32 v130, v140
	v_mov_b32_e32 v131, v136
	v_add_f32_e32 v132, v86, v119
	v_add_f32_e32 v86, v157, v102
	ds_read_b128 v[154:157], v218 offset:80
	ds_read_b128 v[158:161], v218 offset:64
	v_pk_mul_f32 v[130:131], v[114:115], v[130:131]
	v_pk_mul_f32 v[126:127], v[114:115], v[126:127]
	v_add_f32_e32 v94, 0, v130
	v_add_f32_e32 v90, 0, v126
	v_add_f32_e32 v126, v94, v131
	v_lshlrev_b32_e32 v94, 16, v95
	v_and_b32_e32 v95, 0xffff0000, v95
	v_add_f32_e32 v127, v90, v127
	v_pk_fma_f32 v[94:95], v[48:49], v[94:95], v[60:61]
	v_lshlrev_b32_e32 v90, 16, v91
	v_and_b32_e32 v91, 0xffff0000, v91
	v_add_f32_e32 v138, v86, v103
	v_pk_fma_f32 v[90:91], v[52:53], v[90:91], v[94:95]
	v_lshlrev_b32_e32 v86, 16, v87
	v_and_b32_e32 v87, 0xffff0000, v87
	v_pk_fma_f32 v[86:87], v[56:57], v[86:87], v[90:91]
	ds_read_b128 v[234:237], v218 offset:32848
	ds_read_b128 v[238:241], v218 offset:32832
	v_pk_fma_f32 v[86:87], v[44:45], v[98:99], v[86:87]
	ds_read_b128 v[242:245], v222 offset:80
	ds_read_b128 v[246:249], v222 offset:64
	v_mul_f32_e32 v90, 0xbfb8aa3b, v86
	v_exp_f32_e32 v91, v90
	v_mul_f32_e32 v90, 0xbfb8aa3b, v87
	v_exp_f32_e32 v95, v90
	v_mov_b32_e32 v90, v112
	v_add_f32_e32 v91, 1.0, v91
	v_rcp_f32_e32 v94, v91
	v_add_f32_e32 v91, 1.0, v95
	v_rcp_f32_e32 v95, v91
	v_mov_b32_e32 v91, v104
	v_pk_mul_f32 v[90:91], v[90:91], v[98:99]
	v_mov_b32_e32 v136, v141
	v_pk_mul_f32 v[86:87], v[86:87], v[94:95]
	s_nop 0
	s_waitcnt lgkmcnt(8)
	v_mov_b32_e32 v94, v150
	v_mov_b32_e32 v95, v146
	v_pk_mul_f32 v[94:95], v[86:87], v[94:95]
	v_mov_b32_e32 v146, v151
	v_add_f32_e32 v94, v116, v94
	v_add_f32_e32 v139, v94, v95
	s_nop 0
	s_waitcnt lgkmcnt(6)
	v_mov_b32_e32 v94, v142
	v_mov_b32_e32 v95, v122
	v_pk_mul_f32 v[94:95], v[86:87], v[94:95]
	v_mov_b32_e32 v122, v143
	v_add_f32_e32 v94, v120, v94
	v_add_f32_e32 v140, v94, v95
	v_pk_mul_f32 v[94:95], v[86:87], v[146:147]
	v_add_f32_e32 v90, v128, v90
	v_add_f32_e32 v94, v134, v94
	v_add_f32_e32 v134, v94, v95
	v_pk_mul_f32 v[94:95], v[86:87], v[122:123]
	v_mov_b32_e32 v128, v133
	v_add_f32_e32 v94, v135, v94
	v_add_f32_e32 v135, v94, v95
	v_mov_b32_e32 v94, v144
	v_mov_b32_e32 v95, v124
	v_pk_mul_f32 v[94:95], v[86:87], v[94:95]
	v_add_f32_e32 v144, v90, v91
	v_pk_mul_f32 v[90:91], v[114:115], v[136:137]
	v_add_f32_e32 v94, v127, v94
	v_add_f32_e32 v90, 0, v90
	v_add_f32_e32 v143, v94, v95
	v_add_f32_e32 v94, v90, v91
	v_pk_mul_f32 v[90:91], v[114:115], v[128:129]
	v_mov_b32_e32 v116, v121
	v_add_f32_e32 v90, 0, v90
	v_add_f32_e32 v95, v90, v91
	v_pk_mul_f32 v[90:91], v[116:117], v[224:225]
	ds_read_b128 v[114:117], v218 offset:112
	ds_read_b128 v[118:121], v218 offset:96
	v_mov_b32_e32 v102, v152
	v_mov_b32_e32 v103, v148
	v_pk_mul_f32 v[102:103], v[86:87], v[102:103]
	v_add_f32_e32 v90, 0, v90
	v_add_f32_e32 v102, v126, v102
	v_mov_b32_e32 v148, v153
	v_mov_b32_e32 v124, v145
	v_add_f32_e32 v142, v102, v103
	v_add_f32_e32 v102, v90, v91
	v_pk_mul_f32 v[90:91], v[86:87], v[148:149]
	v_pk_mul_f32 v[86:87], v[86:87], v[124:125]
	v_mov_b32_e32 v104, v113
	v_add_f32_e32 v86, v95, v86
	v_add_f32_e32 v136, v86, v87
	v_pk_mul_f32 v[86:87], v[104:105], v[98:99]
	v_add_f32_e32 v90, v94, v90
	v_add_f32_e32 v86, v102, v86
	ds_read_b128 v[102:105], v218 offset:32880
	ds_read_b128 v[110:113], v218 offset:32864
	ds_read_b128 v[122:125], v222 offset:112
	ds_read_b128 v[126:129], v222 offset:96
	v_add_f32_e32 v133, v90, v91
	v_add_f32_e32 v137, v86, v87
	v_lshlrev_b32_e32 v86, 16, v100
	v_and_b32_e32 v87, 0xffff0000, v100
	s_nop 0
	s_waitcnt lgkmcnt(10)
; __device__ __forceinline__ u32x4 pack8(const float* f) { u32x4 w; w.x = pk2(f[0], f[1]); w.y = pk2(f[2], f[3]); w.z = pk2(f[4], f[5]); w.w = pk2(f[6], f[7]); return w; }
; #define MFMA16(a, b, c) __builtin_amdgcn_mfma_f32_16x16x32_bf16((a), (b), (c), 0, 0, 0)
; __device__ __forceinline__ float fsig0(float x) { return __builtin_amdgcn_rcpf(1.0f + __expf(-x)); }
; __device__ void mqk_phase(const Params& p, unsigned char* smem) {
;     ...
;                 for (int i = 0; i < 8; ++i) xmc[i] = xmc[i] * fsig0(xmc[i]);
;                 float qv[8], kv[8], vv[8];
; #pragma unroll
;                 for (int bb = 0; bb < 2; ++bb)
; #pragma unroll
;                     for (int jj = 0; jj < 4; ++jj) { float aq = 0.f, ak = 0.f, av = 0.f;
; #pragma unroll
;                         for (int ii = 0; ii < 4; ++ii) { aq += xmc[4 * bb + ii] * wqp[bb * 16 + ii * 4 + jj]; ak += xmc[4 * bb + ii] * wkp[bb * 16 + ii * 4 + jj]; av += xcur[4 * bb + ii] * wvp[bb * 16 + ii * 4 + jj]; }
;                         qv[4 * bb + jj] = aq; kv[4 * bb + jj] = ak; vv[4 * bb + jj] = av; }
;                 const u32x4 qw = pack8(qv), kw = pack8(kv), vw = pack8(vv);
;                 acc[m] = MFMA16(as_frag(qw), bq, acc[m]); acc[m] = MFMA16(as_frag(kw), bk, acc[m]); acc[m] = MFMA16(as_frag(vw), bv, acc[m]);
; #pragma unroll
;                 for (int i = 0; i < 8; ++i) kv[i] *= 0.0625f;
;                 *(u32x4*)(Q + (size_t)tk * 2048 + c0) = qw; *(u32x4*)(KX + (size_t)tk * 2048 + c0) = pack8(kv);
;             }
	v_mov_b32_e32 v90, v158
	v_mov_b32_e32 v91, v154
	v_pk_mul_f32 v[90:91], v[90:91], v[86:87]
	v_mov_b32_e32 v154, v159
	v_add_f32_e32 v90, 0, v90
	v_add_f32_e32 v100, v90, v91
	v_pk_mul_f32 v[90:91], v[154:155], v[86:87]
	v_lshlrev_b32_e32 v94, 16, v92
	v_add_f32_e32 v90, 0, v90
	v_add_f32_e32 v141, v90, v91
	v_lshlrev_b32_e32 v90, 16, v96
	v_and_b32_e32 v91, 0xffff0000, v96
	v_pk_fma_f32 v[90:91], v[22:23], v[90:91], v[38:39]
	v_and_b32_e32 v95, 0xffff0000, v92
	v_pk_fma_f32 v[90:91], v[26:27], v[94:95], v[90:91]
	v_lshlrev_b32_e32 v94, 16, v88
	v_and_b32_e32 v95, 0xffff0000, v88
	v_pk_fma_f32 v[90:91], v[30:31], v[94:95], v[90:91]
	v_mov_b32_e32 v94, v160
	v_pk_fma_f32 v[90:91], v[34:35], v[86:87], v[90:91]
	v_mov_b32_e32 v95, v156
	v_mul_f32_e32 v88, 0xbfb8aa3b, v90
	v_exp_f32_e32 v88, v88
	v_mul_f32_e32 v92, 0xbfb8aa3b, v91
	v_exp_f32_e32 v92, v92
	s_nop 0
	s_waitcnt lgkmcnt(8)
	v_mov_b32_e32 v130, v240
	v_add_f32_e32 v88, 1.0, v88
	v_rcp_f32_e32 v98, v88
	v_add_f32_e32 v88, 1.0, v92
	v_rcp_f32_e32 v99, v88
	v_mov_b32_e32 v131, v236
	v_pk_mul_f32 v[94:95], v[94:95], v[86:87]
	v_lshlrev_b32_e32 v96, 16, v97
	v_pk_mul_f32 v[90:91], v[90:91], v[98:99]
	v_mov_b32_e32 v98, v238
	v_mov_b32_e32 v99, v234
	v_pk_mul_f32 v[98:99], v[90:91], v[98:99]
	v_mov_b32_e32 v234, v239
	v_add_f32_e32 v92, 0, v98
	v_add_f32_e32 v145, v92, v99
	s_nop 0
	s_waitcnt lgkmcnt(6)
	v_mov_b32_e32 v98, v246
	v_mov_b32_e32 v99, v242
	v_pk_mul_f32 v[98:99], v[90:91], v[98:99]
	v_mov_b32_e32 v242, v247
	v_add_f32_e32 v92, 0, v98
	v_add_f32_e32 v146, v92, v99
	v_pk_mul_f32 v[98:99], v[90:91], v[234:235]
	v_pk_mul_f32 v[130:131], v[90:91], v[130:131]
	v_add_f32_e32 v92, 0, v98
	v_add_f32_e32 v147, v92, v99
	v_pk_mul_f32 v[98:99], v[90:91], v[242:243]
	v_add_f32_e32 v88, 0, v94
	v_add_f32_e32 v92, 0, v98
	v_add_f32_e32 v148, v92, v99
	v_mov_b32_e32 v98, v248
	v_mov_b32_e32 v99, v244
	v_pk_mul_f32 v[98:99], v[90:91], v[98:99]
	v_add_f32_e32 v94, 0, v130
	v_add_f32_e32 v92, 0, v98
	v_add_f32_e32 v130, v94, v131
	v_add_f32_e32 v131, v92, v99
	v_add_f32_e32 v149, v88, v95
	v_lshlrev_b32_e32 v94, 16, v101
	v_and_b32_e32 v95, 0xffff0000, v101
	s_nop 0
	s_waitcnt lgkmcnt(4)
	v_mov_b32_e32 v98, v118
	v_mov_b32_e32 v99, v114
	v_pk_mul_f32 v[98:99], v[98:99], v[94:95]
	v_mov_b32_e32 v114, v119
	v_add_f32_e32 v88, v100, v98
	v_add_f32_e32 v100, v88, v99
	v_pk_mul_f32 v[98:99], v[114:115], v[94:95]
	v_and_b32_e32 v97, 0xffff0000, v97
	v_add_f32_e32 v88, v141, v98
	v_pk_fma_f32 v[96:97], v[24:25], v[96:97], v[40:41]
	v_lshlrev_b32_e32 v92, 16, v93
	v_and_b32_e32 v93, 0xffff0000, v93
	v_add_f32_e32 v101, v88, v99
	v_pk_fma_f32 v[92:93], v[28:29], v[92:93], v[96:97]
	v_lshlrev_b32_e32 v88, 16, v89
	v_and_b32_e32 v89, 0xffff0000, v89
	v_pk_fma_f32 v[88:89], v[32:33], v[88:89], v[92:93]
	v_mov_b32_e32 v236, v241
	v_pk_fma_f32 v[88:89], v[36:37], v[94:95], v[88:89]
	v_mov_b32_e32 v244, v249
	v_mul_f32_e32 v92, 0xbfb8aa3b, v88
	v_exp_f32_e32 v93, v92
	v_mul_f32_e32 v92, 0xbfb8aa3b, v89
	v_exp_f32_e32 v97, v92
	v_mov_b32_e32 v92, v120
	v_add_f32_e32 v93, 1.0, v93
	v_rcp_f32_e32 v96, v93
	v_add_f32_e32 v93, 1.0, v97
	v_rcp_f32_e32 v97, v93
	v_mov_b32_e32 v93, v116
	v_pk_mul_f32 v[92:93], v[92:93], v[94:95]
	v_mov_b32_e32 v156, v161
	v_pk_mul_f32 v[88:89], v[88:89], v[96:97]
	s_nop 0
	s_waitcnt lgkmcnt(2)
	v_mov_b32_e32 v96, v110
	v_mov_b32_e32 v97, v102
	v_pk_mul_f32 v[96:97], v[88:89], v[96:97]
	v_mov_b32_e32 v102, v111
	v_add_f32_e32 v96, v145, v96
	v_add_f32_e32 v110, v96, v97
	s_nop 0
	s_waitcnt lgkmcnt(0)
	v_mov_b32_e32 v96, v126
	v_mov_b32_e32 v97, v122
	v_pk_mul_f32 v[96:97], v[88:89], v[96:97]
	v_mov_b32_e32 v122, v127
	v_add_f32_e32 v96, v146, v96
	v_add_f32_e32 v114, v96, v97
	v_pk_mul_f32 v[96:97], v[88:89], v[102:103]
	v_add_f32_e32 v92, v149, v92
	v_add_f32_e32 v96, v147, v96
	v_add_f32_e32 v102, v96, v97
	v_pk_mul_f32 v[96:97], v[88:89], v[122:123]
	v_pk_mul_f32 v[86:87], v[156:157], v[86:87]
	v_add_f32_e32 v96, v148, v96
	v_add_f32_e32 v111, v96, v97
	v_mov_b32_e32 v96, v128
	v_mov_b32_e32 v97, v124
	v_pk_mul_f32 v[96:97], v[88:89], v[96:97]
	v_mov_b32_e32 v99, v104
	v_add_f32_e32 v96, v131, v96
	v_add_f32_e32 v96, v96, v97
	v_add_f32_e32 v97, v92, v93
	v_pk_mul_f32 v[92:93], v[90:91], v[236:237]
	v_pk_mul_f32 v[90:91], v[90:91], v[244:245]
	v_add_f32_e32 v92, 0, v92
	v_add_f32_e32 v90, 0, v90
	v_add_f32_e32 v86, 0, v86
	v_mov_b32_e32 v104, v113
	v_add_f32_e32 v92, v92, v93
	v_add_f32_e32 v90, v90, v91
	v_add_f32_e32 v91, v86, v87
	v_pk_mul_f32 v[86:87], v[88:89], v[104:105]
	v_mov_b32_e32 v98, v112
	v_add_f32_e32 v86, v92, v86
	v_mov_b32_e32 v124, v129
	v_pk_mul_f32 v[98:99], v[88:89], v[98:99]
	v_add_f32_e32 v92, v86, v87
	v_pk_mul_f32 v[86:87], v[88:89], v[124:125]
	v_add_f32_e32 v98, v130, v98
	v_add_f32_e32 v86, v90, v86
	v_mov_b32_e32 v116, v121
	v_add_f32_e32 v98, v98, v99
	v_add_f32_e32 v99, v86, v87
	v_pk_mul_f32 v[86:87], v[116:117], v[94:95]
	v_mul_f32_e32 v112, 0x3d800000, v96
	v_add_f32_e32 v86, v91, v86
	v_add_f32_e32 v94, v86, v87
	v_cvt_pk_bf16_f32 v86, v139, v134
	v_cvt_pk_bf16_f32 v87, v142, v133
	v_cvt_pk_bf16_f32 v88, v110, v102
	v_cvt_pk_bf16_f32 v89, v98, v92
	v_cvt_pk_bf16_f32 v90, v140, v135
	v_cvt_pk_bf16_f32 v91, v143, v136
	v_cvt_pk_bf16_f32 v92, v114, v111
	v_cvt_pk_bf16_f32 v93, v96, v99
	v_cvt_pk_bf16_f32 v102, v132, v138
	v_cvt_pk_bf16_f32 v103, v144, v137
	v_cvt_pk_bf16_f32 v104, v100, v101
	v_cvt_pk_bf16_f32 v105, v97, v94
	v_mul_f32_e32 v97, 0x3d800000, v140
	v_mul_f32_e32 v98, 0x3d800000, v135
	v_mul_f32_e32 v99, 0x3d800000, v99
	v_lshl_add_u64 v[94:95], v[216:217], 0, v[210:211]
	v_mul_f32_e32 v100, 0x3d800000, v143
	v_mul_f32_e32 v101, 0x3d800000, v136
	v_mul_f32_e32 v110, 0x3d800000, v114
	v_mul_f32_e32 v111, 0x3d800000, v111
	global_store_dwordx4 v[94:95], v[86:89], off
	v_cvt_pk_bf16_f32 v94, v97, v98
	v_cvt_pk_bf16_f32 v95, v100, v101
	v_cvt_pk_bf16_f32 v96, v110, v111
	v_cvt_pk_bf16_f32 v97, v112, v99
	v_lshl_add_u64 v[98:99], v[214:215], 0, v[210:211]
	global_store_dwordx4 v[98:99], v[94:97], off
	ds_read_b128 v[98:101], v218
	s_nop 0
	ds_read_b128 v[94:97], v218 offset:16
	ds_read_b128 v[130:133], v218 offset:32768
	ds_read_b128 v[126:129], v218 offset:32784
	ds_read_b128 v[122:125], v222
	ds_read_b128 v[118:121], v222 offset:16
	v_mfma_f32_16x16x32_bf16 v[2:5], v[86:89], v[18:21], v[2:5]
	s_waitcnt vmcnt(2)
; __device__ __forceinline__ void unpack8(u32x4 w, float* f) { f[0] = bflo(w.x); f[1] = bfhi(w.x); f[2] = bflo(w.y); f[3] = bfhi(w.y); f[4] = bflo(w.z); f[5] = bfhi(w.z); f[6] = bflo(w.w); f[7] = bfhi(w.w); }
; __device__ __forceinline__ u32x4 pack8(const float* f) { u32x4 w; w.x = pk2(f[0], f[1]); w.y = pk2(f[2], f[3]); w.z = pk2(f[4], f[5]); w.w = pk2(f[6], f[7]); return w; }
; #define MFMA16(a, b, c) __builtin_amdgcn_mfma_f32_16x16x32_bf16((a), (b), (c), 0, 0, 0)
; __device__ __forceinline__ float fsig0(float x) { return __builtin_amdgcn_rcpf(1.0f + __expf(-x)); }
; __device__ void mqk_phase(const Params& p, unsigned char* smem) {
;     ...
;                 for (int j = 0; j < 4; ++j) { float xv[8]; unpack8(xraw[j], xv);
; #pragma unroll
;                     for (int i = 0; i < 8; ++i) { xmc[i] += cw[j][i] * xv[i]; if (j == 3) xcur[i] = xv[i]; } }
;                 if (m < 3) {
; #pragma unroll
;                     for (int j = 0; j < 4; ++j) xraw[j] = xnx[j]; }
; #pragma unroll
;                 for (int i = 0; i < 8; ++i) xmc[i] = xmc[i] * fsig0(xmc[i]);
;                 float qv[8], kv[8], vv[8];
; #pragma unroll
;                 for (int bb = 0; bb < 2; ++bb)
; #pragma unroll
;                     for (int jj = 0; jj < 4; ++jj) { float aq = 0.f, ak = 0.f, av = 0.f;
; #pragma unroll
;                         for (int ii = 0; ii < 4; ++ii) { aq += xmc[4 * bb + ii] * wqp[bb * 16 + ii * 4 + jj]; ak += xmc[4 * bb + ii] * wkp[bb * 16 + ii * 4 + jj]; av += xcur[4 * bb + ii] * wvp[bb * 16 + ii * 4 + jj]; }
;                         qv[4 * bb + jj] = aq; kv[4 * bb + jj] = ak; vv[4 * bb + jj] = av; }
;                 const u32x4 qw = pack8(qv), kw = pack8(kv), vw = pack8(vv);
;                 acc[m] = MFMA16(as_frag(qw), bq, acc[m]); acc[m] = MFMA16(as_frag(kw), bk, acc[m]); acc[m] = MFMA16(as_frag(vw), bv, acc[m]);
	v_lshlrev_b32_e32 v134, 16, v82
	v_and_b32_e32 v135, 0xffff0000, v82
	s_nop 0
	s_waitcnt lgkmcnt(5)
	v_mov_b32_e32 v136, v98
	v_mfma_f32_16x16x32_bf16 v[2:5], v[90:93], v[14:17], v[2:5]
	ds_read_b128 v[90:93], v218 offset:32
	ds_read_b128 v[86:89], v218 offset:48
	s_nop 0
	s_waitcnt lgkmcnt(6)
	v_mov_b32_e32 v137, v94
	v_pk_mul_f32 v[136:137], v[136:137], v[134:135]
	v_mfma_f32_16x16x32_bf16 v[2:5], v[102:105], v[10:13], v[2:5]
	ds_read_b128 v[110:113], v218 offset:32816
	ds_read_b128 v[114:117], v218 offset:32800
	ds_read_b128 v[102:105], v222 offset:48
	ds_read_b128 v[106:109], v222 offset:32
	v_mov_b32_e32 v94, v99
	v_add_f32_e32 v82, 0, v136
	v_pk_mul_f32 v[94:95], v[94:95], v[134:135]
	v_add_f32_e32 v98, v82, v137
	v_add_f32_e32 v82, 0, v94
	v_add_f32_e32 v99, v82, v95
	v_lshlrev_b32_e32 v94, 16, v78
	v_and_b32_e32 v95, 0xffff0000, v78
	v_pk_fma_f32 v[46:47], v[46:47], v[94:95], v[58:59]
	v_lshlrev_b32_e32 v58, 16, v74
	v_and_b32_e32 v59, 0xffff0000, v74
	v_pk_fma_f32 v[46:47], v[50:51], v[58:59], v[46:47]
	v_lshlrev_b32_e32 v50, 16, v70
	v_and_b32_e32 v51, 0xffff0000, v70
	v_pk_fma_f32 v[46:47], v[54:55], v[50:51], v[46:47]
	v_lshlrev_b32_e32 v82, 16, v83
	v_pk_fma_f32 v[42:43], v[42:43], v[134:135], v[46:47]
	v_and_b32_e32 v83, 0xffff0000, v83
	v_mul_f32_e32 v46, 0xbfb8aa3b, v42
	v_exp_f32_e32 v47, v46
	v_mul_f32_e32 v46, 0xbfb8aa3b, v43
	v_exp_f32_e32 v51, v46
	v_mov_b32_e32 v46, v100
	v_add_f32_e32 v47, 1.0, v47
	v_rcp_f32_e32 v50, v47
	v_add_f32_e32 v47, 1.0, v51
	v_rcp_f32_e32 v51, v47
	v_mov_b32_e32 v47, v96
	v_pk_mul_f32 v[46:47], v[46:47], v[134:135]
	v_pk_mul_f32 v[94:95], v[42:43], v[50:51]
	s_nop 0
	s_waitcnt lgkmcnt(9)
	v_mov_b32_e32 v42, v130
	s_nop 0
	s_waitcnt lgkmcnt(8)
	v_mov_b32_e32 v43, v126
	v_pk_mul_f32 v[42:43], v[94:95], v[42:43]
	v_mov_b32_e32 v126, v131
	v_add_f32_e32 v42, 0, v42
	v_add_f32_e32 v58, v42, v43
	s_nop 0
	s_waitcnt lgkmcnt(7)
	v_mov_b32_e32 v42, v122
	s_nop 0
	s_waitcnt lgkmcnt(6)
	v_mov_b32_e32 v43, v118
	v_pk_mul_f32 v[42:43], v[94:95], v[42:43]
	v_mov_b32_e32 v118, v123
	v_add_f32_e32 v42, 0, v42
	v_add_f32_e32 v59, v42, v43
	v_pk_mul_f32 v[42:43], v[94:95], v[126:127]
	v_add_f32_e32 v46, 0, v46
	v_add_f32_e32 v42, 0, v42
	v_add_f32_e32 v78, v42, v43
	v_pk_mul_f32 v[42:43], v[94:95], v[118:119]
	v_mov_b32_e32 v50, v132
	v_add_f32_e32 v42, 0, v42
	v_add_f32_e32 v96, v42, v43
	v_mov_b32_e32 v42, v124
	v_mov_b32_e32 v43, v120
	v_pk_mul_f32 v[42:43], v[94:95], v[42:43]
	v_mov_b32_e32 v51, v128
	v_add_f32_e32 v42, 0, v42
	v_add_f32_e32 v118, v42, v43
	v_pk_mul_f32 v[50:51], v[94:95], v[50:51]
	v_add_f32_e32 v74, v46, v47
	v_lshlrev_b32_e32 v46, 16, v75
	v_and_b32_e32 v47, 0xffff0000, v75
	v_add_f32_e32 v50, 0, v50
	v_add_f32_e32 v100, v50, v51
	v_mov_b32_e32 v128, v133
	v_mov_b32_e32 v120, v125
	s_nop 0
	s_waitcnt lgkmcnt(5)
	v_mov_b32_e32 v42, v90
	s_nop 0
	s_waitcnt lgkmcnt(4)
	v_mov_b32_e32 v43, v86
	v_pk_mul_f32 v[42:43], v[42:43], v[82:83]
	v_mov_b32_e32 v86, v91
	v_add_f32_e32 v42, v98, v42
	v_add_f32_e32 v119, v42, v43
	v_pk_mul_f32 v[42:43], v[86:87], v[82:83]
	s_nop 0
	s_waitcnt lgkmcnt(2)
	v_mov_b32_e32 v86, v116
	v_add_f32_e32 v42, v99, v42
	v_add_f32_e32 v122, v42, v43
	v_lshlrev_b32_e32 v42, 16, v79
	v_and_b32_e32 v43, 0xffff0000, v79
	v_pk_fma_f32 v[42:43], v[48:49], v[42:43], v[60:61]
	s_nop 0
	s_waitcnt lgkmcnt(1)
	v_mov_b32_e32 v79, v104
	v_pk_fma_f32 v[42:43], v[52:53], v[46:47], v[42:43]
	v_lshlrev_b32_e32 v46, 16, v71
	v_and_b32_e32 v47, 0xffff0000, v71
	v_pk_fma_f32 v[42:43], v[56:57], v[46:47], v[42:43]
	ds_read_b128 v[46:49], v218 offset:80
	ds_read_b128 v[50:53], v218 offset:64
	v_pk_fma_f32 v[42:43], v[44:45], v[82:83], v[42:43]
	v_mov_b32_e32 v87, v112
	v_mul_f32_e32 v44, 0xbfb8aa3b, v42
	v_exp_f32_e32 v45, v44
	v_mul_f32_e32 v44, 0xbfb8aa3b, v43
	v_exp_f32_e32 v55, v44
	v_mov_b32_e32 v44, v92
	v_add_f32_e32 v45, 1.0, v45
	v_rcp_f32_e32 v54, v45
	v_add_f32_e32 v45, 1.0, v55
	v_rcp_f32_e32 v55, v45
	v_mov_b32_e32 v45, v88
	v_pk_mul_f32 v[70:71], v[44:45], v[82:83]
	v_mov_b32_e32 v112, v117
	v_add_f32_e32 v70, v74, v70
	v_pk_mul_f32 v[74:75], v[42:43], v[54:55]
	v_mov_b32_e32 v42, v114
	v_mov_b32_e32 v43, v110
	v_pk_mul_f32 v[42:43], v[74:75], v[42:43]
	v_mov_b32_e32 v110, v115
	v_add_f32_e32 v42, v58, v42
	v_add_f32_e32 v114, v42, v43
	s_nop 0
	s_waitcnt lgkmcnt(2)
	v_mov_b32_e32 v42, v106
	v_mov_b32_e32 v43, v102
	v_pk_mul_f32 v[42:43], v[74:75], v[42:43]
	v_mov_b32_e32 v102, v107
	v_add_f32_e32 v42, v59, v42
	v_add_f32_e32 v123, v42, v43
	v_pk_mul_f32 v[42:43], v[74:75], v[110:111]
	v_pk_mul_f32 v[58:59], v[74:75], v[102:103]
	v_add_f32_e32 v42, v78, v42
	v_add_f32_e32 v110, v42, v43
	ds_read_b128 v[42:45], v218 offset:32848
	ds_read_b128 v[54:57], v218 offset:32832
	v_add_f32_e32 v58, v96, v58
	v_add_f32_e32 v111, v58, v59
	ds_read_b128 v[58:61], v222 offset:80
	ds_read_b128 v[136:139], v222 offset:64
	v_mov_b32_e32 v78, v108
	v_pk_mul_f32 v[78:79], v[74:75], v[78:79]
	v_pk_mul_f32 v[86:87], v[74:75], v[86:87]
	v_add_f32_e32 v78, v118, v78
	v_add_f32_e32 v78, v78, v79
	v_add_f32_e32 v79, v70, v71
	v_pk_mul_f32 v[70:71], v[94:95], v[128:129]
	v_add_f32_e32 v86, v100, v86
	v_add_f32_e32 v70, 0, v70
	v_add_f32_e32 v115, v86, v87
	v_add_f32_e32 v86, v70, v71
	v_pk_mul_f32 v[70:71], v[94:95], v[120:121]
	v_mov_b32_e32 v96, v101
	v_add_f32_e32 v70, 0, v70
	v_add_f32_e32 v87, v70, v71
	v_pk_mul_f32 v[70:71], v[96:97], v[134:135]
	ds_read_b128 v[94:97], v218 offset:112
	ds_read_b128 v[98:101], v218 offset:96
	v_add_f32_e32 v70, 0, v70
	v_add_f32_e32 v90, v70, v71
	v_pk_mul_f32 v[70:71], v[74:75], v[112:113]
	v_mov_b32_e32 v104, v109
	v_add_f32_e32 v70, v86, v70
	v_add_f32_e32 v112, v70, v71
	v_pk_mul_f32 v[70:71], v[74:75], v[104:105]
	v_mov_b32_e32 v88, v93
	v_add_f32_e32 v70, v87, v70
	v_add_f32_e32 v113, v70, v71
	v_pk_mul_f32 v[70:71], v[88:89], v[82:83]
	s_nop 0
	s_waitcnt lgkmcnt(7)
; __device__ __forceinline__ void unpack8(u32x4 w, float* f) { f[0] = bflo(w.x); f[1] = bfhi(w.x); f[2] = bflo(w.y); f[3] = bfhi(w.y); f[4] = bflo(w.z); f[5] = bfhi(w.z); f[6] = bflo(w.w); f[7] = bfhi(w.w); }
; __device__ __forceinline__ u32x4 pack8(const float* f) { u32x4 w; w.x = pk2(f[0], f[1]); w.y = pk2(f[2], f[3]); w.z = pk2(f[4], f[5]); w.w = pk2(f[6], f[7]); return w; }
; #define MFMA16(a, b, c) __builtin_amdgcn_mfma_f32_16x16x32_bf16((a), (b), (c), 0, 0, 0)
; __device__ __forceinline__ float fsig0(float x) { return __builtin_amdgcn_rcpf(1.0f + __expf(-x)); }
; __device__ void mqk_phase(const Params& p, unsigned char* smem) {
;     ...
;                 for (int j = 0; j < 4; ++j) { float xv[8]; unpack8(xraw[j], xv);
; #pragma unroll
;                     for (int i = 0; i < 8; ++i) { xmc[i] += cw[j][i] * xv[i]; if (j == 3) xcur[i] = xv[i]; } }
;                 if (m < 3) {
; #pragma unroll
;                     for (int j = 0; j < 4; ++j) xraw[j] = xnx[j]; }
; #pragma unroll
;                 for (int i = 0; i < 8; ++i) xmc[i] = xmc[i] * fsig0(xmc[i]);
;                 float qv[8], kv[8], vv[8];
; #pragma unroll
;                 for (int bb = 0; bb < 2; ++bb)
; #pragma unroll
;                     for (int jj = 0; jj < 4; ++jj) { float aq = 0.f, ak = 0.f, av = 0.f;
; #pragma unroll
;                         for (int ii = 0; ii < 4; ++ii) { aq += xmc[4 * bb + ii] * wqp[bb * 16 + ii * 4 + jj]; ak += xmc[4 * bb + ii] * wkp[bb * 16 + ii * 4 + jj]; av += xcur[4 * bb + ii] * wvp[bb * 16 + ii * 4 + jj]; }
;                         qv[4 * bb + jj] = aq; kv[4 * bb + jj] = ak; vv[4 * bb + jj] = av; }
;                 const u32x4 qw = pack8(qv), kw = pack8(kv), vw = pack8(vv);
;                 acc[m] = MFMA16(as_frag(qw), bq, acc[m]); acc[m] = MFMA16(as_frag(kw), bk, acc[m]); acc[m] = MFMA16(as_frag(vw), bv, acc[m]);
; #pragma unroll
;                 for (int i = 0; i < 8; ++i) kv[i] *= 0.0625f;
;                 *(u32x4*)(Q + (size_t)tk * 2048 + c0) = qw; *(u32x4*)(KX + (size_t)tk * 2048 + c0) = pack8(kv);
	v_mov_b32_e32 v75, v46
	v_add_f32_e32 v70, v90, v70
	ds_read_b128 v[86:89], v218 offset:32880
	ds_read_b128 v[90:93], v218 offset:32864
	ds_read_b128 v[102:105], v222 offset:112
	ds_read_b128 v[106:109], v222 offset:96
	v_add_f32_e32 v82, v70, v71
	v_lshlrev_b32_e32 v70, 16, v84
	v_and_b32_e32 v71, 0xffff0000, v84
	s_nop 0
	s_waitcnt lgkmcnt(10)
	v_mov_b32_e32 v74, v50
	v_pk_mul_f32 v[74:75], v[74:75], v[70:71]
	s_nop 0
	v_add_f32_e32 v46, 0, v74
	v_add_f32_e32 v50, v46, v75
	v_mov_b32_e32 v46, v51
	v_pk_mul_f32 v[46:47], v[46:47], v[70:71]
	s_nop 0
	v_add_f32_e32 v46, 0, v46
	v_add_f32_e32 v51, v46, v47
	v_lshlrev_b32_e32 v46, 16, v80
	v_and_b32_e32 v47, 0xffff0000, v80
	v_pk_fma_f32 v[22:23], v[22:23], v[46:47], v[38:39]
	v_lshlrev_b32_e32 v38, 16, v76
	v_and_b32_e32 v39, 0xffff0000, v76
	v_pk_fma_f32 v[22:23], v[26:27], v[38:39], v[22:23]
	v_lshlrev_b32_e32 v26, 16, v72
	v_and_b32_e32 v27, 0xffff0000, v72
	v_pk_fma_f32 v[22:23], v[30:31], v[26:27], v[22:23]
	s_nop 0
	v_pk_fma_f32 v[22:23], v[34:35], v[70:71], v[22:23]
	s_nop 0
	s_waitcnt lgkmcnt(9)
	v_mov_b32_e32 v35, v44
	v_mul_f32_e32 v26, 0xbfb8aa3b, v22
	v_exp_f32_e32 v27, v26
	v_mul_f32_e32 v26, 0xbfb8aa3b, v23
	v_exp_f32_e32 v31, v26
	v_mov_b32_e32 v26, v52
	v_add_f32_e32 v27, 1.0, v27
	v_rcp_f32_e32 v30, v27
	v_add_f32_e32 v27, 1.0, v31
	v_rcp_f32_e32 v31, v27
	v_mov_b32_e32 v27, v48
	s_nop 0
	s_waitcnt lgkmcnt(8)
	v_mov_b32_e32 v34, v56
	v_pk_mul_f32 v[26:27], v[26:27], v[70:71]
	v_pk_mul_f32 v[22:23], v[22:23], v[30:31]
	v_mov_b32_e32 v30, v54
	v_mov_b32_e32 v31, v42
	v_pk_mul_f32 v[30:31], v[22:23], v[30:31]
	v_mov_b32_e32 v42, v55
	v_add_f32_e32 v30, 0, v30
	v_add_f32_e32 v38, v30, v31
	s_nop 0
	s_waitcnt lgkmcnt(6)
	v_mov_b32_e32 v30, v136
	v_mov_b32_e32 v31, v58
	v_pk_mul_f32 v[30:31], v[22:23], v[30:31]
	v_mov_b32_e32 v58, v137
	v_add_f32_e32 v30, 0, v30
	v_add_f32_e32 v39, v30, v31
	v_pk_mul_f32 v[30:31], v[22:23], v[42:43]
	v_pk_mul_f32 v[34:35], v[22:23], v[34:35]
	v_add_f32_e32 v30, 0, v30
	v_add_f32_e32 v42, v30, v31
	v_pk_mul_f32 v[30:31], v[22:23], v[58:59]
	v_add_f32_e32 v26, 0, v26
	v_add_f32_e32 v30, 0, v30
	v_add_f32_e32 v43, v30, v31
	v_mov_b32_e32 v30, v138
	v_mov_b32_e32 v31, v60
	v_pk_mul_f32 v[30:31], v[22:23], v[30:31]
	v_add_f32_e32 v34, 0, v34
	v_add_f32_e32 v30, 0, v30
	v_add_f32_e32 v34, v34, v35
	v_add_f32_e32 v35, v30, v31
	v_add_f32_e32 v44, v26, v27
	v_lshlrev_b32_e32 v26, 16, v85
	v_and_b32_e32 v27, 0xffff0000, v85
	s_nop 0
	s_waitcnt lgkmcnt(4)
	v_mov_b32_e32 v30, v98
	v_mov_b32_e32 v31, v94
	v_pk_mul_f32 v[30:31], v[30:31], v[26:27]
	v_mov_b32_e32 v94, v99
	v_add_f32_e32 v30, v50, v30
	v_add_f32_e32 v46, v30, v31
	v_pk_mul_f32 v[30:31], v[94:95], v[26:27]
	v_mov_b32_e32 v60, v139
	v_add_f32_e32 v30, v51, v30
	v_add_f32_e32 v47, v30, v31
	v_lshlrev_b32_e32 v30, 16, v81
	v_and_b32_e32 v31, 0xffff0000, v81
	v_pk_fma_f32 v[24:25], v[24:25], v[30:31], v[40:41]
	v_lshlrev_b32_e32 v30, 16, v77
	v_and_b32_e32 v31, 0xffff0000, v77
	v_pk_fma_f32 v[24:25], v[28:29], v[30:31], v[24:25]
	v_lshlrev_b32_e32 v28, 16, v73
	v_and_b32_e32 v29, 0xffff0000, v73
	v_pk_fma_f32 v[24:25], v[32:33], v[28:29], v[24:25]
	s_nop 0
	s_waitcnt lgkmcnt(2)
	v_mov_b32_e32 v32, v92
	v_pk_fma_f32 v[24:25], v[36:37], v[26:27], v[24:25]
	v_mov_b32_e32 v33, v88
	v_mul_f32_e32 v28, 0xbfb8aa3b, v24
	v_exp_f32_e32 v29, v28
	v_mul_f32_e32 v28, 0xbfb8aa3b, v25
	v_exp_f32_e32 v31, v28
	v_mov_b32_e32 v28, v100
	v_add_f32_e32 v29, 1.0, v29
	v_rcp_f32_e32 v30, v29
	v_add_f32_e32 v29, 1.0, v31
	v_rcp_f32_e32 v31, v29
	v_mov_b32_e32 v29, v96
	v_pk_mul_f32 v[28:29], v[28:29], v[26:27]
	v_mov_b32_e32 v48, v53
	v_pk_mul_f32 v[24:25], v[24:25], v[30:31]
	v_mov_b32_e32 v30, v90
	v_mov_b32_e32 v31, v86
	v_pk_mul_f32 v[30:31], v[24:25], v[30:31]
	v_mov_b32_e32 v86, v91
	v_add_f32_e32 v30, v38, v30
	v_add_f32_e32 v36, v30, v31
	s_nop 0
	s_waitcnt lgkmcnt(0)
	v_mov_b32_e32 v30, v106
	v_mov_b32_e32 v31, v102
	v_pk_mul_f32 v[30:31], v[24:25], v[30:31]
	v_mov_b32_e32 v102, v107
	v_add_f32_e32 v30, v39, v30
	v_add_f32_e32 v37, v30, v31
	v_pk_mul_f32 v[30:31], v[24:25], v[86:87]
	v_add_f32_e32 v28, v44, v28
	v_add_f32_e32 v30, v42, v30
	v_add_f32_e32 v38, v30, v31
	v_pk_mul_f32 v[30:31], v[24:25], v[102:103]
	v_mov_b32_e32 v44, v57
	v_add_f32_e32 v30, v43, v30
	v_add_f32_e32 v39, v30, v31
	v_mov_b32_e32 v30, v108
	v_mov_b32_e32 v31, v104
	v_pk_mul_f32 v[30:31], v[24:25], v[30:31]
	v_pk_mul_f32 v[32:33], v[24:25], v[32:33]
	v_add_f32_e32 v30, v35, v30
	v_add_f32_e32 v30, v30, v31
	v_add_f32_e32 v31, v28, v29
	v_pk_mul_f32 v[28:29], v[22:23], v[44:45]
	v_pk_mul_f32 v[22:23], v[22:23], v[60:61]
	v_add_f32_e32 v28, 0, v28
	v_add_f32_e32 v22, 0, v22
	v_add_f32_e32 v28, v28, v29
	v_add_f32_e32 v29, v22, v23
	v_pk_mul_f32 v[22:23], v[48:49], v[70:71]
	v_add_f32_e32 v32, v34, v32
	v_add_f32_e32 v22, 0, v22
	v_mov_b32_e32 v88, v93
	v_add_f32_e32 v32, v32, v33
	v_add_f32_e32 v33, v22, v23
	v_pk_mul_f32 v[22:23], v[24:25], v[88:89]
	v_mov_b32_e32 v104, v109
	v_add_f32_e32 v22, v28, v22
	v_add_f32_e32 v28, v22, v23
	v_pk_mul_f32 v[22:23], v[24:25], v[104:105]
	v_mov_b32_e32 v96, v101
	v_add_f32_e32 v22, v29, v22
	v_add_f32_e32 v34, v22, v23
	v_pk_mul_f32 v[22:23], v[96:97], v[26:27]
	s_nop 0
	v_add_f32_e32 v22, v33, v22
	v_add_f32_e32 v33, v22, v23
	v_cvt_pk_bf16_f32 v22, v114, v110
	v_cvt_pk_bf16_f32 v23, v115, v112
	v_cvt_pk_bf16_f32 v24, v36, v38
	v_cvt_pk_bf16_f32 v25, v32, v28
	v_cvt_pk_bf16_f32 v26, v123, v111
	v_cvt_pk_bf16_f32 v27, v78, v113
	v_cvt_pk_bf16_f32 v28, v37, v39
	v_cvt_pk_bf16_f32 v29, v30, v34
	s_nop 0
	v_mfma_f32_16x16x32_bf16 v[6:9], v[22:25], v[18:21], v[6:9]
	v_cvt_pk_bf16_f32 v18, v119, v122
	v_cvt_pk_bf16_f32 v19, v79, v82
	v_cvt_pk_bf16_f32 v20, v46, v47
	v_mfma_f32_16x16x32_bf16 v[6:9], v[26:29], v[14:17], v[6:9]
	v_cvt_pk_bf16_f32 v21, v31, v33
	v_mul_f32_e32 v14, 0x3d800000, v78
	v_mul_f32_e32 v15, 0x3d800000, v113
	v_mfma_f32_16x16x32_bf16 v[6:9], v[18:21], v[10:13], v[6:9]
	v_lshl_add_u64 v[10:11], v[216:217], 0, v[212:213]
	v_mul_f32_e32 v12, 0x3d800000, v123
	v_mul_f32_e32 v13, 0x3d800000, v111
	global_store_dwordx4 v[10:11], v[22:25], off
	v_cvt_pk_bf16_f32 v10, v12, v13
	v_cvt_pk_bf16_f32 v11, v14, v15
	v_lshl_add_u64 v[14:15], v[214:215], 0, v[212:213]
	v_mul_f32_e32 v16, 0x3d800000, v37
	v_mul_f32_e32 v17, 0x3d800000, v39
	v_mul_f32_e32 v18, 0x3d800000, v30
	v_mul_f32_e32 v19, 0x3d800000, v34
	v_cvt_pk_bf16_f32 v12, v16, v17
	v_cvt_pk_bf16_f32 v13, v18, v19
	global_store_dwordx4 v[14:15], v[10:13], off
	s_cbranch_scc1 .LBB0_307
